# hand-written outproj and down GEMMs: skewed LDS/MFMA pipeline, residual+gate loads prefetched at tile start
# speedup vs baseline: 1.0579x; 1.0306x over previous
.LBB0_43:
	s_waitcnt vmcnt(0) lgkmcnt(0)
	v_readlane_b32 s2, v253, 0
	v_readlane_b32 s3, v254, 4
	v_readlane_b32 s30, v252, 0
	v_readlane_b32 s31, v252, 1
	v_readlane_b32 s24, v252, 2
	v_readlane_b32 s25, v252, 3
	v_readlane_b32 s82, v252, 8
	v_readlane_b32 s80, v254, 56
	v_readlane_b32 s81, v254, 57
	s_mov_b32 s18, s98
	s_mov_b32 s19, s99
	s_mov_b32 s36, 0xb0000
	s_and_b32 s77, s2, 7
	s_lshl_b32 s77, s77, 2
	s_lshr_b32 s78, s2, 3
	s_lshr_b32 s79, s3, 3
	s_cmp_gt_u32 s78, 31
	s_cbranch_scc1 .LBB0_56
	v_and_b32_e32 v170, 15, v1
	v_bfe_u32 v171, v1, 4, 2
	v_bfe_u32 v172, v1, 6, 1
	v_lshrrev_b32_e32 v173, 7, v1
	v_and_b32_e32 v162, 7, v170
	v_xor_b32_e32 v162, v162, v171
	v_lshlrev_b32_e32 v162, 4, v162
	v_lshlrev_b32_e32 v200, 13, v173
	v_lshl_add_u32 v200, v170, 7, v200
	v_add_u32_e32 v200, v200, v162
	v_xor_b32_e32 v201, 64, v200
	v_lshlrev_b32_e32 v202, 13, v172
	v_lshl_add_u32 v202, v170, 7, v202
	v_add_u32_e32 v202, v202, v162
	v_add_u32_e32 v202, 0x8000, v202
	v_xor_b32_e32 v203, 64, v202
	v_lshl_add_u32 v162, v173, 6, v170
	v_lshlrev_b32_e32 v172, 6, v172
	v_lshl_add_u32 v172, v171, 2, v172
	v_lshlrev_b32_e32 v190, 2, v172
	v_lshlrev_b32_e32 v206, 11, v162
	v_lshl_add_u32 v206, v172, 1, v206
	v_add_u32_e32 v207, 0x8000, v206
	v_add_u32_e32 v208, 0x10000, v206
	v_add_u32_e32 v209, 0x18000, v206
	v_lshlrev_b32_e32 v210, 12, v162
	v_add_u32_e32 v210, v210, v190
	v_add_u32_e32 v211, 0x10000, v210
	v_add_u32_e32 v168, 0x20000, v210
	v_add_u32_e32 v169, 0x30000, v210
	v_lshrrev_b32_e32 v170, 3, v1
	v_and_b32_e32 v171, 7, v1
	v_and_b32_e32 v173, 7, v170
	v_xor_b32_e32 v171, v171, v173
	v_lshlrev_b32_e32 v171, 4, v171
	v_mul_u32_u24_e32 v196, 0x1600, v170
	v_add_u32_e32 v196, v196, v171
	v_add_u32_e32 v197, 0x58000, v196
	v_add_u32_e32 v198, 0xb0000, v196
	v_add_u32_e32 v199, 0x108000, v196
	v_lshrrev_b32_e32 v170, 6, v1
	v_lshlrev_b32_e32 v170, 10, v170
	s_nop 0
	v_readfirstlane_b32 s76, v170
.Ldn_tile:
	s_and_b32 s0, s78, 3
	s_or_b32 s0, s0, s77
	s_lshr_b32 s1, s78, 2
	s_lshl_b32 s1, s1, 7
	s_lshl_b32 s2, s0, 8
	s_mul_i32 s3, s2, 0x1600
	s_add_u32 s68, s18, s3
	s_addc_u32 s69, s19, 0
	s_mul_i32 s3, s1, 0x1600
	s_add_u32 s70, s80, s3
	s_addc_u32 s71, s81, 0
	s_lshl_b32 s3, s2, 11
	s_lshl_b32 s12, s1, 1
	s_add_u32 s3, s3, s12
	s_add_u32 s74, s24, s3
	s_addc_u32 s75, s25, 0
	s_add_i32 s12, s0, -12
	s_lshr_b32 s12, s12, 2
	s_cmp_lt_u32 s0, 16
	s_cselect_b32 s12, 0, s12
	s_cselect_b32 s14, s52, s54
	s_cselect_b32 s15, s53, s55
	s_mul_i32 s13, s82, 5
	s_add_i32 s12, s12, s13
	s_mul_i32 s12, s12, 0x6000
	s_add_u32 s12, s12, 0x5000
	s_lshl_b32 s13, s1, 2
	s_add_u32 s12, s12, s13
	s_add_u32 s72, s30, s12
	s_addc_u32 s73, s31, 0
	s_and_b32 s12, s0, 15
	s_lshl_b32 s12, s12, 20
	s_add_u32 s12, s12, s13
	s_add_u32 s14, s14, s12
	s_addc_u32 s15, s15, 0
	s_add_u32 m0, s76, 0x0
	s_nop 0
	global_load_lds_dwordx4 v196, s[68:69]
	s_add_u32 m0, s76, 0x2000
	s_nop 0
	global_load_lds_dwordx4 v197, s[68:69]
	s_add_u32 m0, s76, 0x4000
	s_nop 0
	global_load_lds_dwordx4 v198, s[68:69]
	s_add_u32 m0, s76, 0x6000
	s_nop 0
	global_load_lds_dwordx4 v199, s[68:69]
	s_add_u32 m0, s76, 0x8000
	s_nop 0
	global_load_lds_dwordx4 v196, s[70:71]
	s_add_u32 m0, s76, 0xa000
	s_nop 0
	global_load_lds_dwordx4 v197, s[70:71]
	s_add_u32 s68, s68, 0x80
	s_addc_u32 s69, s69, 0
	s_add_u32 s70, s70, 0x80
	s_addc_u32 s71, s71, 0
	s_add_u32 m0, s76, 0xc000
	s_nop 0
	global_load_lds_dwordx4 v196, s[68:69]
	s_add_u32 m0, s76, 0xe000
	s_nop 0
	global_load_lds_dwordx4 v197, s[68:69]
	s_add_u32 m0, s76, 0x10000
	s_nop 0
	global_load_lds_dwordx4 v198, s[68:69]
	s_add_u32 m0, s76, 0x12000
	s_nop 0
	global_load_lds_dwordx4 v199, s[68:69]
	s_add_u32 m0, s76, 0x14000
	s_nop 0
	global_load_lds_dwordx4 v196, s[70:71]
	s_add_u32 m0, s76, 0x16000
	s_nop 0
	global_load_lds_dwordx4 v197, s[70:71]
	s_add_u32 s68, s68, 0x80
	s_addc_u32 s69, s69, 0
	s_add_u32 s70, s70, 0x80
	s_addc_u32 s71, s71, 0
	global_load_dwordx4 v[174:177], v190, s[72:73] offset:0
	global_load_dwordx4 v[178:181], v190, s[72:73] offset:64
	global_load_dwordx4 v[182:185], v190, s[72:73] offset:128
	global_load_dwordx4 v[186:189], v190, s[72:73] offset:192
	global_load_dwordx2 v[66:67], v206, s[74:75] offset:0
	global_load_dwordx2 v[70:71], v206, s[74:75] offset:32
	global_load_dwordx2 v[74:75], v206, s[74:75] offset:64
	global_load_dwordx2 v[78:79], v206, s[74:75] offset:96
	global_load_dwordx2 v[82:83], v207, s[74:75] offset:0
	global_load_dwordx2 v[86:87], v207, s[74:75] offset:32
	global_load_dwordx2 v[90:91], v207, s[74:75] offset:64
	global_load_dwordx2 v[94:95], v207, s[74:75] offset:96
	global_load_dwordx2 v[98:99], v208, s[74:75] offset:0
	global_load_dwordx2 v[102:103], v208, s[74:75] offset:32
	global_load_dwordx2 v[106:107], v208, s[74:75] offset:64
	global_load_dwordx2 v[110:111], v208, s[74:75] offset:96
	global_load_dwordx2 v[114:115], v209, s[74:75] offset:0
	global_load_dwordx2 v[118:119], v209, s[74:75] offset:32
	global_load_dwordx2 v[122:123], v209, s[74:75] offset:64
	global_load_dwordx2 v[126:127], v209, s[74:75] offset:96
	s_waitcnt vmcnt(26)
	s_waitcnt lgkmcnt(0)
	s_barrier
	v_add_u32_e32 v204, 0x0, v200
	v_add_u32_e32 v205, 0x0, v202
	ds_read_b128 v[130:133], v204 offset:0
	ds_read_b128 v[134:137], v204 offset:2048
	ds_read_b128 v[138:141], v204 offset:4096
	ds_read_b128 v[142:145], v204 offset:6144
	ds_read_b128 v[146:149], v205 offset:0
	ds_read_b128 v[150:153], v205 offset:2048
	ds_read_b128 v[154:157], v205 offset:4096
	ds_read_b128 v[158:161], v205 offset:6144
	s_add_u32 m0, s76, 0x18000
	s_nop 0
	global_load_lds_dwordx4 v196, s[68:69]
	s_add_u32 m0, s76, 0x1a000
	s_nop 0
	global_load_lds_dwordx4 v197, s[68:69]
	s_add_u32 m0, s76, 0x1c000
	s_nop 0
	global_load_lds_dwordx4 v198, s[68:69]
	s_add_u32 m0, s76, 0x1e000
	s_nop 0
	global_load_lds_dwordx4 v199, s[68:69]
	s_add_u32 m0, s76, 0x20000
	s_nop 0
	global_load_lds_dwordx4 v196, s[70:71]
	s_add_u32 m0, s76, 0x22000
	s_nop 0
	global_load_lds_dwordx4 v197, s[70:71]
	s_add_u32 s68, s68, 0x80
	s_addc_u32 s69, s69, 0
	s_add_u32 s70, s70, 0x80
	s_addc_u32 s71, s71, 0
	s_waitcnt lgkmcnt(0)
	v_add_u32_e32 v204, 0x0, v201
	v_add_u32_e32 v205, 0x0, v203
	ds_read_b128 v[212:215], v204 offset:0
	ds_read_b128 v[216:219], v204 offset:2048
	ds_read_b128 v[220:223], v204 offset:4096
	ds_read_b128 v[224:227], v204 offset:6144
	ds_read_b128 v[228:231], v205 offset:0
	ds_read_b128 v[232:235], v205 offset:2048
	ds_read_b128 v[236:239], v205 offset:4096
	ds_read_b128 v[240:243], v205 offset:6144
	v_mfma_f32_16x16x32_bf16 v[2:5], v[146:149], v[130:133], 0
	v_mfma_f32_16x16x32_bf16 v[6:9], v[150:153], v[130:133], 0
	v_mfma_f32_16x16x32_bf16 v[10:13], v[154:157], v[130:133], 0
	v_mfma_f32_16x16x32_bf16 v[14:17], v[158:161], v[130:133], 0
	v_mfma_f32_16x16x32_bf16 v[18:21], v[146:149], v[134:137], 0
	v_mfma_f32_16x16x32_bf16 v[22:25], v[150:153], v[134:137], 0
	v_mfma_f32_16x16x32_bf16 v[26:29], v[154:157], v[134:137], 0
	v_mfma_f32_16x16x32_bf16 v[30:33], v[158:161], v[134:137], 0
	v_mfma_f32_16x16x32_bf16 v[34:37], v[146:149], v[138:141], 0
	v_mfma_f32_16x16x32_bf16 v[38:41], v[150:153], v[138:141], 0
	v_mfma_f32_16x16x32_bf16 v[42:45], v[154:157], v[138:141], 0
	v_mfma_f32_16x16x32_bf16 v[46:49], v[158:161], v[138:141], 0
	v_mfma_f32_16x16x32_bf16 v[50:53], v[146:149], v[142:145], 0
	v_mfma_f32_16x16x32_bf16 v[54:57], v[150:153], v[142:145], 0
	v_mfma_f32_16x16x32_bf16 v[58:61], v[154:157], v[142:145], 0
	v_mfma_f32_16x16x32_bf16 v[62:65], v[158:161], v[142:145], 0
	s_waitcnt vmcnt(26)
	s_waitcnt lgkmcnt(0)
	s_barrier
	v_add_u32_e32 v204, 0xc000, v200
	v_add_u32_e32 v205, 0xc000, v202
	ds_read_b128 v[130:133], v204 offset:0
	ds_read_b128 v[134:137], v204 offset:2048
	ds_read_b128 v[138:141], v204 offset:4096
	ds_read_b128 v[142:145], v204 offset:6144
	ds_read_b128 v[146:149], v205 offset:0
	ds_read_b128 v[150:153], v205 offset:2048
	ds_read_b128 v[154:157], v205 offset:4096
	ds_read_b128 v[158:161], v205 offset:6144
	v_mfma_f32_16x16x32_bf16 v[2:5], v[228:231], v[212:215], v[2:5]
	v_mfma_f32_16x16x32_bf16 v[6:9], v[232:235], v[212:215], v[6:9]
	s_add_u32 m0, s76, 0x0
	s_nop 0
	global_load_lds_dwordx4 v196, s[68:69]
	v_mfma_f32_16x16x32_bf16 v[10:13], v[236:239], v[212:215], v[10:13]
	v_mfma_f32_16x16x32_bf16 v[14:17], v[240:243], v[212:215], v[14:17]
	s_add_u32 m0, s76, 0x2000
	s_nop 0
	global_load_lds_dwordx4 v197, s[68:69]
	v_mfma_f32_16x16x32_bf16 v[18:21], v[228:231], v[216:219], v[18:21]
	v_mfma_f32_16x16x32_bf16 v[22:25], v[232:235], v[216:219], v[22:25]
	s_add_u32 m0, s76, 0x4000
	s_nop 0
	global_load_lds_dwordx4 v198, s[68:69]
	v_mfma_f32_16x16x32_bf16 v[26:29], v[236:239], v[216:219], v[26:29]
	v_mfma_f32_16x16x32_bf16 v[30:33], v[240:243], v[216:219], v[30:33]
	s_add_u32 m0, s76, 0x6000
	s_nop 0
	global_load_lds_dwordx4 v199, s[68:69]
	v_mfma_f32_16x16x32_bf16 v[34:37], v[228:231], v[220:223], v[34:37]
	v_mfma_f32_16x16x32_bf16 v[38:41], v[232:235], v[220:223], v[38:41]
	s_add_u32 m0, s76, 0x8000
	s_nop 0
	global_load_lds_dwordx4 v196, s[70:71]
	v_mfma_f32_16x16x32_bf16 v[42:45], v[236:239], v[220:223], v[42:45]
	v_mfma_f32_16x16x32_bf16 v[46:49], v[240:243], v[220:223], v[46:49]
	s_add_u32 m0, s76, 0xa000
	s_nop 0
	global_load_lds_dwordx4 v197, s[70:71]
	v_mfma_f32_16x16x32_bf16 v[50:53], v[228:231], v[224:227], v[50:53]
	v_mfma_f32_16x16x32_bf16 v[54:57], v[232:235], v[224:227], v[54:57]
	s_add_u32 s68, s68, 0x80
	s_addc_u32 s69, s69, 0
	s_add_u32 s70, s70, 0x80
	s_addc_u32 s71, s71, 0
	v_mfma_f32_16x16x32_bf16 v[58:61], v[236:239], v[224:227], v[58:61]
	v_mfma_f32_16x16x32_bf16 v[62:65], v[240:243], v[224:227], v[62:65]
	s_waitcnt lgkmcnt(0)
	v_add_u32_e32 v204, 0xc000, v201
	v_add_u32_e32 v205, 0xc000, v203
	ds_read_b128 v[212:215], v204 offset:0
	ds_read_b128 v[216:219], v204 offset:2048
	ds_read_b128 v[220:223], v204 offset:4096
	ds_read_b128 v[224:227], v204 offset:6144
	ds_read_b128 v[228:231], v205 offset:0
	ds_read_b128 v[232:235], v205 offset:2048
	ds_read_b128 v[236:239], v205 offset:4096
	ds_read_b128 v[240:243], v205 offset:6144
	v_mfma_f32_16x16x32_bf16 v[2:5], v[146:149], v[130:133], v[2:5]
	v_mfma_f32_16x16x32_bf16 v[6:9], v[150:153], v[130:133], v[6:9]
	v_mfma_f32_16x16x32_bf16 v[10:13], v[154:157], v[130:133], v[10:13]
	v_mfma_f32_16x16x32_bf16 v[14:17], v[158:161], v[130:133], v[14:17]
	v_mfma_f32_16x16x32_bf16 v[18:21], v[146:149], v[134:137], v[18:21]
	v_mfma_f32_16x16x32_bf16 v[22:25], v[150:153], v[134:137], v[22:25]
	v_mfma_f32_16x16x32_bf16 v[26:29], v[154:157], v[134:137], v[26:29]
	v_mfma_f32_16x16x32_bf16 v[30:33], v[158:161], v[134:137], v[30:33]
	v_mfma_f32_16x16x32_bf16 v[34:37], v[146:149], v[138:141], v[34:37]
	v_mfma_f32_16x16x32_bf16 v[38:41], v[150:153], v[138:141], v[38:41]
	v_mfma_f32_16x16x32_bf16 v[42:45], v[154:157], v[138:141], v[42:45]
	v_mfma_f32_16x16x32_bf16 v[46:49], v[158:161], v[138:141], v[46:49]
	v_mfma_f32_16x16x32_bf16 v[50:53], v[146:149], v[142:145], v[50:53]
	v_mfma_f32_16x16x32_bf16 v[54:57], v[150:153], v[142:145], v[54:57]
	v_mfma_f32_16x16x32_bf16 v[58:61], v[154:157], v[142:145], v[58:61]
	v_mfma_f32_16x16x32_bf16 v[62:65], v[158:161], v[142:145], v[62:65]
	s_mov_b32 s16, 13
.Ldn_kloop:
	s_waitcnt vmcnt(6)
	s_waitcnt lgkmcnt(0)
	s_barrier
	v_add_u32_e32 v204, 0x18000, v200
	v_add_u32_e32 v205, 0x18000, v202
	ds_read_b128 v[130:133], v204 offset:0
	ds_read_b128 v[134:137], v204 offset:2048
	ds_read_b128 v[138:141], v204 offset:4096
	ds_read_b128 v[142:145], v204 offset:6144
	ds_read_b128 v[146:149], v205 offset:0
	ds_read_b128 v[150:153], v205 offset:2048
	ds_read_b128 v[154:157], v205 offset:4096
	ds_read_b128 v[158:161], v205 offset:6144
	v_mfma_f32_16x16x32_bf16 v[2:5], v[228:231], v[212:215], v[2:5]
	v_mfma_f32_16x16x32_bf16 v[6:9], v[232:235], v[212:215], v[6:9]
	s_add_u32 m0, s76, 0xc000
	s_nop 0
	global_load_lds_dwordx4 v196, s[68:69]
	v_mfma_f32_16x16x32_bf16 v[10:13], v[236:239], v[212:215], v[10:13]
	v_mfma_f32_16x16x32_bf16 v[14:17], v[240:243], v[212:215], v[14:17]
	s_add_u32 m0, s76, 0xe000
	s_nop 0
	global_load_lds_dwordx4 v197, s[68:69]
	v_mfma_f32_16x16x32_bf16 v[18:21], v[228:231], v[216:219], v[18:21]
	v_mfma_f32_16x16x32_bf16 v[22:25], v[232:235], v[216:219], v[22:25]
	s_add_u32 m0, s76, 0x10000
	s_nop 0
	global_load_lds_dwordx4 v198, s[68:69]
	v_mfma_f32_16x16x32_bf16 v[26:29], v[236:239], v[216:219], v[26:29]
	v_mfma_f32_16x16x32_bf16 v[30:33], v[240:243], v[216:219], v[30:33]
	s_add_u32 m0, s76, 0x12000
	s_nop 0
	global_load_lds_dwordx4 v199, s[68:69]
	v_mfma_f32_16x16x32_bf16 v[34:37], v[228:231], v[220:223], v[34:37]
	v_mfma_f32_16x16x32_bf16 v[38:41], v[232:235], v[220:223], v[38:41]
	s_add_u32 m0, s76, 0x14000
	s_nop 0
	global_load_lds_dwordx4 v196, s[70:71]
	v_mfma_f32_16x16x32_bf16 v[42:45], v[236:239], v[220:223], v[42:45]
	v_mfma_f32_16x16x32_bf16 v[46:49], v[240:243], v[220:223], v[46:49]
	s_add_u32 m0, s76, 0x16000
	s_nop 0
	global_load_lds_dwordx4 v197, s[70:71]
	v_mfma_f32_16x16x32_bf16 v[50:53], v[228:231], v[224:227], v[50:53]
	v_mfma_f32_16x16x32_bf16 v[54:57], v[232:235], v[224:227], v[54:57]
	s_add_u32 s68, s68, 0x80
	s_addc_u32 s69, s69, 0
	s_add_u32 s70, s70, 0x80
	s_addc_u32 s71, s71, 0
	v_mfma_f32_16x16x32_bf16 v[58:61], v[236:239], v[224:227], v[58:61]
	v_mfma_f32_16x16x32_bf16 v[62:65], v[240:243], v[224:227], v[62:65]
	s_waitcnt lgkmcnt(0)
	v_add_u32_e32 v204, 0x18000, v201
	v_add_u32_e32 v205, 0x18000, v203
	ds_read_b128 v[212:215], v204 offset:0
	ds_read_b128 v[216:219], v204 offset:2048
	ds_read_b128 v[220:223], v204 offset:4096
	ds_read_b128 v[224:227], v204 offset:6144
	ds_read_b128 v[228:231], v205 offset:0
	ds_read_b128 v[232:235], v205 offset:2048
	ds_read_b128 v[236:239], v205 offset:4096
	ds_read_b128 v[240:243], v205 offset:6144
	v_mfma_f32_16x16x32_bf16 v[2:5], v[146:149], v[130:133], v[2:5]
	v_mfma_f32_16x16x32_bf16 v[6:9], v[150:153], v[130:133], v[6:9]
	v_mfma_f32_16x16x32_bf16 v[10:13], v[154:157], v[130:133], v[10:13]
	v_mfma_f32_16x16x32_bf16 v[14:17], v[158:161], v[130:133], v[14:17]
	v_mfma_f32_16x16x32_bf16 v[18:21], v[146:149], v[134:137], v[18:21]
	v_mfma_f32_16x16x32_bf16 v[22:25], v[150:153], v[134:137], v[22:25]
	v_mfma_f32_16x16x32_bf16 v[26:29], v[154:157], v[134:137], v[26:29]
	v_mfma_f32_16x16x32_bf16 v[30:33], v[158:161], v[134:137], v[30:33]
	v_mfma_f32_16x16x32_bf16 v[34:37], v[146:149], v[138:141], v[34:37]
	v_mfma_f32_16x16x32_bf16 v[38:41], v[150:153], v[138:141], v[38:41]
	v_mfma_f32_16x16x32_bf16 v[42:45], v[154:157], v[138:141], v[42:45]
	v_mfma_f32_16x16x32_bf16 v[46:49], v[158:161], v[138:141], v[46:49]
	v_mfma_f32_16x16x32_bf16 v[50:53], v[146:149], v[142:145], v[50:53]
	v_mfma_f32_16x16x32_bf16 v[54:57], v[150:153], v[142:145], v[54:57]
	v_mfma_f32_16x16x32_bf16 v[58:61], v[154:157], v[142:145], v[58:61]
	v_mfma_f32_16x16x32_bf16 v[62:65], v[158:161], v[142:145], v[62:65]
	s_waitcnt vmcnt(6)
	s_waitcnt lgkmcnt(0)
	s_barrier
	v_add_u32_e32 v204, 0x0, v200
	v_add_u32_e32 v205, 0x0, v202
	ds_read_b128 v[130:133], v204 offset:0
	ds_read_b128 v[134:137], v204 offset:2048
	ds_read_b128 v[138:141], v204 offset:4096
	ds_read_b128 v[142:145], v204 offset:6144
	ds_read_b128 v[146:149], v205 offset:0
	ds_read_b128 v[150:153], v205 offset:2048
	ds_read_b128 v[154:157], v205 offset:4096
	ds_read_b128 v[158:161], v205 offset:6144
	v_mfma_f32_16x16x32_bf16 v[2:5], v[228:231], v[212:215], v[2:5]
	v_mfma_f32_16x16x32_bf16 v[6:9], v[232:235], v[212:215], v[6:9]
	s_add_u32 m0, s76, 0x18000
	s_nop 0
	global_load_lds_dwordx4 v196, s[68:69]
	v_mfma_f32_16x16x32_bf16 v[10:13], v[236:239], v[212:215], v[10:13]
	v_mfma_f32_16x16x32_bf16 v[14:17], v[240:243], v[212:215], v[14:17]
	s_add_u32 m0, s76, 0x1a000
	s_nop 0
	global_load_lds_dwordx4 v197, s[68:69]
	v_mfma_f32_16x16x32_bf16 v[18:21], v[228:231], v[216:219], v[18:21]
	v_mfma_f32_16x16x32_bf16 v[22:25], v[232:235], v[216:219], v[22:25]
	s_add_u32 m0, s76, 0x1c000
	s_nop 0
	global_load_lds_dwordx4 v198, s[68:69]
	v_mfma_f32_16x16x32_bf16 v[26:29], v[236:239], v[216:219], v[26:29]
	v_mfma_f32_16x16x32_bf16 v[30:33], v[240:243], v[216:219], v[30:33]
	s_add_u32 m0, s76, 0x1e000
	s_nop 0
	global_load_lds_dwordx4 v199, s[68:69]
	v_mfma_f32_16x16x32_bf16 v[34:37], v[228:231], v[220:223], v[34:37]
	v_mfma_f32_16x16x32_bf16 v[38:41], v[232:235], v[220:223], v[38:41]
	s_add_u32 m0, s76, 0x20000
	s_nop 0
	global_load_lds_dwordx4 v196, s[70:71]
	v_mfma_f32_16x16x32_bf16 v[42:45], v[236:239], v[220:223], v[42:45]
	v_mfma_f32_16x16x32_bf16 v[46:49], v[240:243], v[220:223], v[46:49]
	s_add_u32 m0, s76, 0x22000
	s_nop 0
	global_load_lds_dwordx4 v197, s[70:71]
	v_mfma_f32_16x16x32_bf16 v[50:53], v[228:231], v[224:227], v[50:53]
	v_mfma_f32_16x16x32_bf16 v[54:57], v[232:235], v[224:227], v[54:57]
	s_add_u32 s68, s68, 0x80
	s_addc_u32 s69, s69, 0
	s_add_u32 s70, s70, 0x80
	s_addc_u32 s71, s71, 0
	v_mfma_f32_16x16x32_bf16 v[58:61], v[236:239], v[224:227], v[58:61]
	v_mfma_f32_16x16x32_bf16 v[62:65], v[240:243], v[224:227], v[62:65]
	s_waitcnt lgkmcnt(0)
	v_add_u32_e32 v204, 0x0, v201
	v_add_u32_e32 v205, 0x0, v203
	ds_read_b128 v[212:215], v204 offset:0
	ds_read_b128 v[216:219], v204 offset:2048
	ds_read_b128 v[220:223], v204 offset:4096
	ds_read_b128 v[224:227], v204 offset:6144
	ds_read_b128 v[228:231], v205 offset:0
	ds_read_b128 v[232:235], v205 offset:2048
	ds_read_b128 v[236:239], v205 offset:4096
	ds_read_b128 v[240:243], v205 offset:6144
	v_mfma_f32_16x16x32_bf16 v[2:5], v[146:149], v[130:133], v[2:5]
	v_mfma_f32_16x16x32_bf16 v[6:9], v[150:153], v[130:133], v[6:9]
	v_mfma_f32_16x16x32_bf16 v[10:13], v[154:157], v[130:133], v[10:13]
	v_mfma_f32_16x16x32_bf16 v[14:17], v[158:161], v[130:133], v[14:17]
	v_mfma_f32_16x16x32_bf16 v[18:21], v[146:149], v[134:137], v[18:21]
	v_mfma_f32_16x16x32_bf16 v[22:25], v[150:153], v[134:137], v[22:25]
	v_mfma_f32_16x16x32_bf16 v[26:29], v[154:157], v[134:137], v[26:29]
	v_mfma_f32_16x16x32_bf16 v[30:33], v[158:161], v[134:137], v[30:33]
	v_mfma_f32_16x16x32_bf16 v[34:37], v[146:149], v[138:141], v[34:37]
	v_mfma_f32_16x16x32_bf16 v[38:41], v[150:153], v[138:141], v[38:41]
	v_mfma_f32_16x16x32_bf16 v[42:45], v[154:157], v[138:141], v[42:45]
	v_mfma_f32_16x16x32_bf16 v[46:49], v[158:161], v[138:141], v[46:49]
	v_mfma_f32_16x16x32_bf16 v[50:53], v[146:149], v[142:145], v[50:53]
	v_mfma_f32_16x16x32_bf16 v[54:57], v[150:153], v[142:145], v[54:57]
	v_mfma_f32_16x16x32_bf16 v[58:61], v[154:157], v[142:145], v[58:61]
	v_mfma_f32_16x16x32_bf16 v[62:65], v[158:161], v[142:145], v[62:65]
	s_waitcnt vmcnt(6)
	s_waitcnt lgkmcnt(0)
	s_barrier
	v_add_u32_e32 v204, 0xc000, v200
	v_add_u32_e32 v205, 0xc000, v202
	ds_read_b128 v[130:133], v204 offset:0
	ds_read_b128 v[134:137], v204 offset:2048
	ds_read_b128 v[138:141], v204 offset:4096
	ds_read_b128 v[142:145], v204 offset:6144
	ds_read_b128 v[146:149], v205 offset:0
	ds_read_b128 v[150:153], v205 offset:2048
	ds_read_b128 v[154:157], v205 offset:4096
	ds_read_b128 v[158:161], v205 offset:6144
	v_mfma_f32_16x16x32_bf16 v[2:5], v[228:231], v[212:215], v[2:5]
	v_mfma_f32_16x16x32_bf16 v[6:9], v[232:235], v[212:215], v[6:9]
	s_add_u32 m0, s76, 0x0
	s_nop 0
	global_load_lds_dwordx4 v196, s[68:69]
	v_mfma_f32_16x16x32_bf16 v[10:13], v[236:239], v[212:215], v[10:13]
	v_mfma_f32_16x16x32_bf16 v[14:17], v[240:243], v[212:215], v[14:17]
	s_add_u32 m0, s76, 0x2000
	s_nop 0
	global_load_lds_dwordx4 v197, s[68:69]
	v_mfma_f32_16x16x32_bf16 v[18:21], v[228:231], v[216:219], v[18:21]
	v_mfma_f32_16x16x32_bf16 v[22:25], v[232:235], v[216:219], v[22:25]
	s_add_u32 m0, s76, 0x4000
	s_nop 0
	global_load_lds_dwordx4 v198, s[68:69]
	v_mfma_f32_16x16x32_bf16 v[26:29], v[236:239], v[216:219], v[26:29]
	v_mfma_f32_16x16x32_bf16 v[30:33], v[240:243], v[216:219], v[30:33]
	s_add_u32 m0, s76, 0x6000
	s_nop 0
	global_load_lds_dwordx4 v199, s[68:69]
	v_mfma_f32_16x16x32_bf16 v[34:37], v[228:231], v[220:223], v[34:37]
	v_mfma_f32_16x16x32_bf16 v[38:41], v[232:235], v[220:223], v[38:41]
	s_add_u32 m0, s76, 0x8000
	s_nop 0
	global_load_lds_dwordx4 v196, s[70:71]
	v_mfma_f32_16x16x32_bf16 v[42:45], v[236:239], v[220:223], v[42:45]
	v_mfma_f32_16x16x32_bf16 v[46:49], v[240:243], v[220:223], v[46:49]
	s_add_u32 m0, s76, 0xa000
	s_nop 0
	global_load_lds_dwordx4 v197, s[70:71]
	v_mfma_f32_16x16x32_bf16 v[50:53], v[228:231], v[224:227], v[50:53]
	v_mfma_f32_16x16x32_bf16 v[54:57], v[232:235], v[224:227], v[54:57]
	s_add_u32 s68, s68, 0x80
	s_addc_u32 s69, s69, 0
	s_add_u32 s70, s70, 0x80
	s_addc_u32 s71, s71, 0
	v_mfma_f32_16x16x32_bf16 v[58:61], v[236:239], v[224:227], v[58:61]
	v_mfma_f32_16x16x32_bf16 v[62:65], v[240:243], v[224:227], v[62:65]
	s_waitcnt lgkmcnt(0)
	v_add_u32_e32 v204, 0xc000, v201
	v_add_u32_e32 v205, 0xc000, v203
	ds_read_b128 v[212:215], v204 offset:0
	ds_read_b128 v[216:219], v204 offset:2048
	ds_read_b128 v[220:223], v204 offset:4096
	ds_read_b128 v[224:227], v204 offset:6144
	ds_read_b128 v[228:231], v205 offset:0
	ds_read_b128 v[232:235], v205 offset:2048
	ds_read_b128 v[236:239], v205 offset:4096
	ds_read_b128 v[240:243], v205 offset:6144
	v_mfma_f32_16x16x32_bf16 v[2:5], v[146:149], v[130:133], v[2:5]
	v_mfma_f32_16x16x32_bf16 v[6:9], v[150:153], v[130:133], v[6:9]
	v_mfma_f32_16x16x32_bf16 v[10:13], v[154:157], v[130:133], v[10:13]
	v_mfma_f32_16x16x32_bf16 v[14:17], v[158:161], v[130:133], v[14:17]
	v_mfma_f32_16x16x32_bf16 v[18:21], v[146:149], v[134:137], v[18:21]
	v_mfma_f32_16x16x32_bf16 v[22:25], v[150:153], v[134:137], v[22:25]
	v_mfma_f32_16x16x32_bf16 v[26:29], v[154:157], v[134:137], v[26:29]
	v_mfma_f32_16x16x32_bf16 v[30:33], v[158:161], v[134:137], v[30:33]
	v_mfma_f32_16x16x32_bf16 v[34:37], v[146:149], v[138:141], v[34:37]
	v_mfma_f32_16x16x32_bf16 v[38:41], v[150:153], v[138:141], v[38:41]
	v_mfma_f32_16x16x32_bf16 v[42:45], v[154:157], v[138:141], v[42:45]
	v_mfma_f32_16x16x32_bf16 v[46:49], v[158:161], v[138:141], v[46:49]
	v_mfma_f32_16x16x32_bf16 v[50:53], v[146:149], v[142:145], v[50:53]
	v_mfma_f32_16x16x32_bf16 v[54:57], v[150:153], v[142:145], v[54:57]
	v_mfma_f32_16x16x32_bf16 v[58:61], v[154:157], v[142:145], v[58:61]
	v_mfma_f32_16x16x32_bf16 v[62:65], v[158:161], v[142:145], v[62:65]
	s_add_i32 s16, s16, -1
	s_cmp_lg_u32 s16, 0
	s_cbranch_scc1 .Ldn_kloop
	s_waitcnt vmcnt(6)
	s_waitcnt lgkmcnt(0)
	s_barrier
	v_add_u32_e32 v204, 0x18000, v200
	v_add_u32_e32 v205, 0x18000, v202
	ds_read_b128 v[130:133], v204 offset:0
	ds_read_b128 v[134:137], v204 offset:2048
	ds_read_b128 v[138:141], v204 offset:4096
	ds_read_b128 v[142:145], v204 offset:6144
	ds_read_b128 v[146:149], v205 offset:0
	ds_read_b128 v[150:153], v205 offset:2048
	ds_read_b128 v[154:157], v205 offset:4096
	ds_read_b128 v[158:161], v205 offset:6144
	v_mfma_f32_16x16x32_bf16 v[2:5], v[228:231], v[212:215], v[2:5]
	v_mfma_f32_16x16x32_bf16 v[6:9], v[232:235], v[212:215], v[6:9]
	s_add_u32 m0, s76, 0xc000
	s_nop 0
	global_load_lds_dwordx4 v196, s[68:69]
	v_mfma_f32_16x16x32_bf16 v[10:13], v[236:239], v[212:215], v[10:13]
	v_mfma_f32_16x16x32_bf16 v[14:17], v[240:243], v[212:215], v[14:17]
	s_add_u32 m0, s76, 0xe000
	s_nop 0
	global_load_lds_dwordx4 v197, s[68:69]
	v_mfma_f32_16x16x32_bf16 v[18:21], v[228:231], v[216:219], v[18:21]
	v_mfma_f32_16x16x32_bf16 v[22:25], v[232:235], v[216:219], v[22:25]
	s_add_u32 m0, s76, 0x10000
	s_nop 0
	global_load_lds_dwordx4 v198, s[68:69]
	v_mfma_f32_16x16x32_bf16 v[26:29], v[236:239], v[216:219], v[26:29]
	v_mfma_f32_16x16x32_bf16 v[30:33], v[240:243], v[216:219], v[30:33]
	s_add_u32 m0, s76, 0x12000
	s_nop 0
	global_load_lds_dwordx4 v199, s[68:69]
	v_mfma_f32_16x16x32_bf16 v[34:37], v[228:231], v[220:223], v[34:37]
	v_mfma_f32_16x16x32_bf16 v[38:41], v[232:235], v[220:223], v[38:41]
	s_add_u32 m0, s76, 0x14000
	s_nop 0
	global_load_lds_dwordx4 v196, s[70:71]
	v_mfma_f32_16x16x32_bf16 v[42:45], v[236:239], v[220:223], v[42:45]
	v_mfma_f32_16x16x32_bf16 v[46:49], v[240:243], v[220:223], v[46:49]
	s_add_u32 m0, s76, 0x16000
	s_nop 0
	global_load_lds_dwordx4 v197, s[70:71]
	v_mfma_f32_16x16x32_bf16 v[50:53], v[228:231], v[224:227], v[50:53]
	v_mfma_f32_16x16x32_bf16 v[54:57], v[232:235], v[224:227], v[54:57]
	s_add_u32 s68, s68, 0x80
	s_addc_u32 s69, s69, 0
	s_add_u32 s70, s70, 0x80
	s_addc_u32 s71, s71, 0
	v_mfma_f32_16x16x32_bf16 v[58:61], v[236:239], v[224:227], v[58:61]
	v_mfma_f32_16x16x32_bf16 v[62:65], v[240:243], v[224:227], v[62:65]
	s_waitcnt lgkmcnt(0)
	v_add_u32_e32 v204, 0x18000, v201
	v_add_u32_e32 v205, 0x18000, v203
	ds_read_b128 v[212:215], v204 offset:0
	ds_read_b128 v[216:219], v204 offset:2048
	ds_read_b128 v[220:223], v204 offset:4096
	ds_read_b128 v[224:227], v204 offset:6144
	ds_read_b128 v[228:231], v205 offset:0
	ds_read_b128 v[232:235], v205 offset:2048
	ds_read_b128 v[236:239], v205 offset:4096
	ds_read_b128 v[240:243], v205 offset:6144
	v_mfma_f32_16x16x32_bf16 v[2:5], v[146:149], v[130:133], v[2:5]
	v_mfma_f32_16x16x32_bf16 v[6:9], v[150:153], v[130:133], v[6:9]
	v_mfma_f32_16x16x32_bf16 v[10:13], v[154:157], v[130:133], v[10:13]
	v_mfma_f32_16x16x32_bf16 v[14:17], v[158:161], v[130:133], v[14:17]
	v_mfma_f32_16x16x32_bf16 v[18:21], v[146:149], v[134:137], v[18:21]
	v_mfma_f32_16x16x32_bf16 v[22:25], v[150:153], v[134:137], v[22:25]
	v_mfma_f32_16x16x32_bf16 v[26:29], v[154:157], v[134:137], v[26:29]
	v_mfma_f32_16x16x32_bf16 v[30:33], v[158:161], v[134:137], v[30:33]
	v_mfma_f32_16x16x32_bf16 v[34:37], v[146:149], v[138:141], v[34:37]
	v_mfma_f32_16x16x32_bf16 v[38:41], v[150:153], v[138:141], v[38:41]
	v_mfma_f32_16x16x32_bf16 v[42:45], v[154:157], v[138:141], v[42:45]
	v_mfma_f32_16x16x32_bf16 v[46:49], v[158:161], v[138:141], v[46:49]
	v_mfma_f32_16x16x32_bf16 v[50:53], v[146:149], v[142:145], v[50:53]
	v_mfma_f32_16x16x32_bf16 v[54:57], v[150:153], v[142:145], v[54:57]
	v_mfma_f32_16x16x32_bf16 v[58:61], v[154:157], v[142:145], v[58:61]
	v_mfma_f32_16x16x32_bf16 v[62:65], v[158:161], v[142:145], v[62:65]
	s_waitcnt vmcnt(6)
	s_waitcnt lgkmcnt(0)
	s_barrier
	v_add_u32_e32 v204, 0x0, v200
	v_add_u32_e32 v205, 0x0, v202
	ds_read_b128 v[130:133], v204 offset:0
	ds_read_b128 v[134:137], v204 offset:2048
	ds_read_b128 v[138:141], v204 offset:4096
	ds_read_b128 v[142:145], v204 offset:6144
	ds_read_b128 v[146:149], v205 offset:0
	ds_read_b128 v[150:153], v205 offset:2048
	ds_read_b128 v[154:157], v205 offset:4096
	ds_read_b128 v[158:161], v205 offset:6144
	v_mfma_f32_16x16x32_bf16 v[2:5], v[228:231], v[212:215], v[2:5]
	v_mfma_f32_16x16x32_bf16 v[6:9], v[232:235], v[212:215], v[6:9]
	v_mfma_f32_16x16x32_bf16 v[10:13], v[236:239], v[212:215], v[10:13]
	v_mfma_f32_16x16x32_bf16 v[14:17], v[240:243], v[212:215], v[14:17]
	v_mfma_f32_16x16x32_bf16 v[18:21], v[228:231], v[216:219], v[18:21]
	v_mfma_f32_16x16x32_bf16 v[22:25], v[232:235], v[216:219], v[22:25]
	v_mfma_f32_16x16x32_bf16 v[26:29], v[236:239], v[216:219], v[26:29]
	v_mfma_f32_16x16x32_bf16 v[30:33], v[240:243], v[216:219], v[30:33]
	v_mfma_f32_16x16x32_bf16 v[34:37], v[228:231], v[220:223], v[34:37]
	v_mfma_f32_16x16x32_bf16 v[38:41], v[232:235], v[220:223], v[38:41]
	v_mfma_f32_16x16x32_bf16 v[42:45], v[236:239], v[220:223], v[42:45]
	v_mfma_f32_16x16x32_bf16 v[46:49], v[240:243], v[220:223], v[46:49]
	v_mfma_f32_16x16x32_bf16 v[50:53], v[228:231], v[224:227], v[50:53]
	v_mfma_f32_16x16x32_bf16 v[54:57], v[232:235], v[224:227], v[54:57]
	v_mfma_f32_16x16x32_bf16 v[58:61], v[236:239], v[224:227], v[58:61]
	v_mfma_f32_16x16x32_bf16 v[62:65], v[240:243], v[224:227], v[62:65]
	s_waitcnt lgkmcnt(0)
	v_add_u32_e32 v204, 0x0, v201
	v_add_u32_e32 v205, 0x0, v203
	ds_read_b128 v[212:215], v204 offset:0
	ds_read_b128 v[216:219], v204 offset:2048
	ds_read_b128 v[220:223], v204 offset:4096
	ds_read_b128 v[224:227], v204 offset:6144
	ds_read_b128 v[228:231], v205 offset:0
	ds_read_b128 v[232:235], v205 offset:2048
	ds_read_b128 v[236:239], v205 offset:4096
	ds_read_b128 v[240:243], v205 offset:6144
	v_mfma_f32_16x16x32_bf16 v[2:5], v[146:149], v[130:133], v[2:5]
	v_mfma_f32_16x16x32_bf16 v[6:9], v[150:153], v[130:133], v[6:9]
	v_mfma_f32_16x16x32_bf16 v[10:13], v[154:157], v[130:133], v[10:13]
	v_mfma_f32_16x16x32_bf16 v[14:17], v[158:161], v[130:133], v[14:17]
	v_mfma_f32_16x16x32_bf16 v[18:21], v[146:149], v[134:137], v[18:21]
	v_mfma_f32_16x16x32_bf16 v[22:25], v[150:153], v[134:137], v[22:25]
	v_mfma_f32_16x16x32_bf16 v[26:29], v[154:157], v[134:137], v[26:29]
	v_mfma_f32_16x16x32_bf16 v[30:33], v[158:161], v[134:137], v[30:33]
	v_mfma_f32_16x16x32_bf16 v[34:37], v[146:149], v[138:141], v[34:37]
	v_mfma_f32_16x16x32_bf16 v[38:41], v[150:153], v[138:141], v[38:41]
	v_mfma_f32_16x16x32_bf16 v[42:45], v[154:157], v[138:141], v[42:45]
	v_mfma_f32_16x16x32_bf16 v[46:49], v[158:161], v[138:141], v[46:49]
	v_mfma_f32_16x16x32_bf16 v[50:53], v[146:149], v[142:145], v[50:53]
	v_mfma_f32_16x16x32_bf16 v[54:57], v[150:153], v[142:145], v[54:57]
	v_mfma_f32_16x16x32_bf16 v[58:61], v[154:157], v[142:145], v[58:61]
	v_mfma_f32_16x16x32_bf16 v[62:65], v[158:161], v[142:145], v[62:65]
	s_waitcnt vmcnt(0)
	s_waitcnt lgkmcnt(0)
	s_barrier
	v_add_u32_e32 v204, 0xc000, v200
	v_add_u32_e32 v205, 0xc000, v202
	ds_read_b128 v[130:133], v204 offset:0
	ds_read_b128 v[134:137], v204 offset:2048
	ds_read_b128 v[138:141], v204 offset:4096
	ds_read_b128 v[142:145], v204 offset:6144
	ds_read_b128 v[146:149], v205 offset:0
	ds_read_b128 v[150:153], v205 offset:2048
	ds_read_b128 v[154:157], v205 offset:4096
	ds_read_b128 v[158:161], v205 offset:6144
	v_mfma_f32_16x16x32_bf16 v[2:5], v[228:231], v[212:215], v[2:5]
	v_mfma_f32_16x16x32_bf16 v[6:9], v[232:235], v[212:215], v[6:9]
	v_mfma_f32_16x16x32_bf16 v[10:13], v[236:239], v[212:215], v[10:13]
	v_mfma_f32_16x16x32_bf16 v[14:17], v[240:243], v[212:215], v[14:17]
	v_mfma_f32_16x16x32_bf16 v[18:21], v[228:231], v[216:219], v[18:21]
	v_mfma_f32_16x16x32_bf16 v[22:25], v[232:235], v[216:219], v[22:25]
	v_mfma_f32_16x16x32_bf16 v[26:29], v[236:239], v[216:219], v[26:29]
	v_mfma_f32_16x16x32_bf16 v[30:33], v[240:243], v[216:219], v[30:33]
	v_mfma_f32_16x16x32_bf16 v[34:37], v[228:231], v[220:223], v[34:37]
	v_mfma_f32_16x16x32_bf16 v[38:41], v[232:235], v[220:223], v[38:41]
	v_mfma_f32_16x16x32_bf16 v[42:45], v[236:239], v[220:223], v[42:45]
	v_mfma_f32_16x16x32_bf16 v[46:49], v[240:243], v[220:223], v[46:49]
	v_mfma_f32_16x16x32_bf16 v[50:53], v[228:231], v[224:227], v[50:53]
	v_mfma_f32_16x16x32_bf16 v[54:57], v[232:235], v[224:227], v[54:57]
	v_mfma_f32_16x16x32_bf16 v[58:61], v[236:239], v[224:227], v[58:61]
	v_mfma_f32_16x16x32_bf16 v[62:65], v[240:243], v[224:227], v[62:65]
	s_waitcnt lgkmcnt(0)
	v_add_u32_e32 v204, 0xc000, v201
	v_add_u32_e32 v205, 0xc000, v203
	ds_read_b128 v[212:215], v204 offset:0
	ds_read_b128 v[216:219], v204 offset:2048
	ds_read_b128 v[220:223], v204 offset:4096
	ds_read_b128 v[224:227], v204 offset:6144
	ds_read_b128 v[228:231], v205 offset:0
	ds_read_b128 v[232:235], v205 offset:2048
	ds_read_b128 v[236:239], v205 offset:4096
	ds_read_b128 v[240:243], v205 offset:6144
	v_mfma_f32_16x16x32_bf16 v[2:5], v[146:149], v[130:133], v[2:5]
	v_mfma_f32_16x16x32_bf16 v[6:9], v[150:153], v[130:133], v[6:9]
	v_mfma_f32_16x16x32_bf16 v[10:13], v[154:157], v[130:133], v[10:13]
	v_mfma_f32_16x16x32_bf16 v[14:17], v[158:161], v[130:133], v[14:17]
	v_mfma_f32_16x16x32_bf16 v[18:21], v[146:149], v[134:137], v[18:21]
	v_mfma_f32_16x16x32_bf16 v[22:25], v[150:153], v[134:137], v[22:25]
	v_mfma_f32_16x16x32_bf16 v[26:29], v[154:157], v[134:137], v[26:29]
	v_mfma_f32_16x16x32_bf16 v[30:33], v[158:161], v[134:137], v[30:33]
	v_mfma_f32_16x16x32_bf16 v[34:37], v[146:149], v[138:141], v[34:37]
	v_mfma_f32_16x16x32_bf16 v[38:41], v[150:153], v[138:141], v[38:41]
	v_mfma_f32_16x16x32_bf16 v[42:45], v[154:157], v[138:141], v[42:45]
	v_mfma_f32_16x16x32_bf16 v[46:49], v[158:161], v[138:141], v[46:49]
	v_mfma_f32_16x16x32_bf16 v[50:53], v[146:149], v[142:145], v[50:53]
	v_mfma_f32_16x16x32_bf16 v[54:57], v[150:153], v[142:145], v[54:57]
	v_mfma_f32_16x16x32_bf16 v[58:61], v[154:157], v[142:145], v[58:61]
	v_mfma_f32_16x16x32_bf16 v[62:65], v[158:161], v[142:145], v[62:65]
	s_waitcnt lgkmcnt(0)
	v_mfma_f32_16x16x32_bf16 v[2:5], v[228:231], v[212:215], v[2:5]
	v_mfma_f32_16x16x32_bf16 v[6:9], v[232:235], v[212:215], v[6:9]
	v_mfma_f32_16x16x32_bf16 v[10:13], v[236:239], v[212:215], v[10:13]
	v_mfma_f32_16x16x32_bf16 v[14:17], v[240:243], v[212:215], v[14:17]
	v_mfma_f32_16x16x32_bf16 v[18:21], v[228:231], v[216:219], v[18:21]
	v_mfma_f32_16x16x32_bf16 v[22:25], v[232:235], v[216:219], v[22:25]
	v_mfma_f32_16x16x32_bf16 v[26:29], v[236:239], v[216:219], v[26:29]
	v_mfma_f32_16x16x32_bf16 v[30:33], v[240:243], v[216:219], v[30:33]
	v_mfma_f32_16x16x32_bf16 v[34:37], v[228:231], v[220:223], v[34:37]
	v_mfma_f32_16x16x32_bf16 v[38:41], v[232:235], v[220:223], v[38:41]
	v_mfma_f32_16x16x32_bf16 v[42:45], v[236:239], v[220:223], v[42:45]
	v_mfma_f32_16x16x32_bf16 v[46:49], v[240:243], v[220:223], v[46:49]
	v_mfma_f32_16x16x32_bf16 v[50:53], v[228:231], v[224:227], v[50:53]
	v_mfma_f32_16x16x32_bf16 v[54:57], v[232:235], v[224:227], v[54:57]
	v_mfma_f32_16x16x32_bf16 v[58:61], v[236:239], v[224:227], v[58:61]
	v_mfma_f32_16x16x32_bf16 v[62:65], v[240:243], v[224:227], v[62:65]
	s_waitcnt vmcnt(0)
	s_nop 7
	v_lshlrev_b32_e32 v68, 16, v67
	v_and_b32_e32 v69, 0xffff0000, v67
	v_and_b32_e32 v67, 0xffff0000, v66
	v_lshlrev_b32_e32 v66, 16, v66
	v_pk_fma_f32 v[4:5], v[4:5], v[176:177], v[68:69]
	v_pk_fma_f32 v[2:3], v[2:3], v[174:175], v[66:67]
	s_nop 0
	v_cvt_pk_bf16_f32 v2, v2, v3
	v_cvt_pk_bf16_f32 v3, v4, v5
	global_store_dwordx2 v206, v[2:3], s[74:75] offset:0
	v_lshlrev_b32_e32 v72, 16, v71
	v_and_b32_e32 v73, 0xffff0000, v71
	v_and_b32_e32 v71, 0xffff0000, v70
	v_lshlrev_b32_e32 v70, 16, v70
	v_pk_fma_f32 v[8:9], v[8:9], v[180:181], v[72:73]
	v_pk_fma_f32 v[6:7], v[6:7], v[178:179], v[70:71]
	s_nop 0
	v_cvt_pk_bf16_f32 v6, v6, v7
	v_cvt_pk_bf16_f32 v7, v8, v9
	global_store_dwordx2 v206, v[6:7], s[74:75] offset:32
	v_lshlrev_b32_e32 v76, 16, v75
	v_and_b32_e32 v77, 0xffff0000, v75
	v_and_b32_e32 v75, 0xffff0000, v74
	v_lshlrev_b32_e32 v74, 16, v74
	v_pk_fma_f32 v[12:13], v[12:13], v[184:185], v[76:77]
	v_pk_fma_f32 v[10:11], v[10:11], v[182:183], v[74:75]
	s_nop 0
	v_cvt_pk_bf16_f32 v10, v10, v11
	v_cvt_pk_bf16_f32 v11, v12, v13
	global_store_dwordx2 v206, v[10:11], s[74:75] offset:64
	v_lshlrev_b32_e32 v80, 16, v79
	v_and_b32_e32 v81, 0xffff0000, v79
	v_and_b32_e32 v79, 0xffff0000, v78
	v_lshlrev_b32_e32 v78, 16, v78
	v_pk_fma_f32 v[16:17], v[16:17], v[188:189], v[80:81]
	v_pk_fma_f32 v[14:15], v[14:15], v[186:187], v[78:79]
	s_nop 0
	v_cvt_pk_bf16_f32 v14, v14, v15
	v_cvt_pk_bf16_f32 v15, v16, v17
	global_store_dwordx2 v206, v[14:15], s[74:75] offset:96
	v_lshlrev_b32_e32 v84, 16, v83
	v_and_b32_e32 v85, 0xffff0000, v83
	v_and_b32_e32 v83, 0xffff0000, v82
	v_lshlrev_b32_e32 v82, 16, v82
	v_pk_fma_f32 v[20:21], v[20:21], v[176:177], v[84:85]
	v_pk_fma_f32 v[18:19], v[18:19], v[174:175], v[82:83]
	s_nop 0
	v_cvt_pk_bf16_f32 v18, v18, v19
	v_cvt_pk_bf16_f32 v19, v20, v21
	global_store_dwordx2 v207, v[18:19], s[74:75] offset:0
	v_lshlrev_b32_e32 v88, 16, v87
	v_and_b32_e32 v89, 0xffff0000, v87
	v_and_b32_e32 v87, 0xffff0000, v86
	v_lshlrev_b32_e32 v86, 16, v86
	v_pk_fma_f32 v[24:25], v[24:25], v[180:181], v[88:89]
	v_pk_fma_f32 v[22:23], v[22:23], v[178:179], v[86:87]
	s_nop 0
	v_cvt_pk_bf16_f32 v22, v22, v23
	v_cvt_pk_bf16_f32 v23, v24, v25
	global_store_dwordx2 v207, v[22:23], s[74:75] offset:32
	v_lshlrev_b32_e32 v92, 16, v91
	v_and_b32_e32 v93, 0xffff0000, v91
	v_and_b32_e32 v91, 0xffff0000, v90
	v_lshlrev_b32_e32 v90, 16, v90
	v_pk_fma_f32 v[28:29], v[28:29], v[184:185], v[92:93]
	v_pk_fma_f32 v[26:27], v[26:27], v[182:183], v[90:91]
	s_nop 0
	v_cvt_pk_bf16_f32 v26, v26, v27
	v_cvt_pk_bf16_f32 v27, v28, v29
	global_store_dwordx2 v207, v[26:27], s[74:75] offset:64
	v_lshlrev_b32_e32 v96, 16, v95
	v_and_b32_e32 v97, 0xffff0000, v95
	v_and_b32_e32 v95, 0xffff0000, v94
	v_lshlrev_b32_e32 v94, 16, v94
	v_pk_fma_f32 v[32:33], v[32:33], v[188:189], v[96:97]
	v_pk_fma_f32 v[30:31], v[30:31], v[186:187], v[94:95]
	s_nop 0
	v_cvt_pk_bf16_f32 v30, v30, v31
	v_cvt_pk_bf16_f32 v31, v32, v33
	global_store_dwordx2 v207, v[30:31], s[74:75] offset:96
	v_lshlrev_b32_e32 v100, 16, v99
	v_and_b32_e32 v101, 0xffff0000, v99
	v_and_b32_e32 v99, 0xffff0000, v98
	v_lshlrev_b32_e32 v98, 16, v98
	v_pk_fma_f32 v[36:37], v[36:37], v[176:177], v[100:101]
	v_pk_fma_f32 v[34:35], v[34:35], v[174:175], v[98:99]
	s_nop 0
	v_cvt_pk_bf16_f32 v34, v34, v35
	v_cvt_pk_bf16_f32 v35, v36, v37
	global_store_dwordx2 v208, v[34:35], s[74:75] offset:0
	v_lshlrev_b32_e32 v104, 16, v103
	v_and_b32_e32 v105, 0xffff0000, v103
	v_and_b32_e32 v103, 0xffff0000, v102
	v_lshlrev_b32_e32 v102, 16, v102
	v_pk_fma_f32 v[40:41], v[40:41], v[180:181], v[104:105]
	v_pk_fma_f32 v[38:39], v[38:39], v[178:179], v[102:103]
	s_nop 0
	v_cvt_pk_bf16_f32 v38, v38, v39
	v_cvt_pk_bf16_f32 v39, v40, v41
	global_store_dwordx2 v208, v[38:39], s[74:75] offset:32
	v_lshlrev_b32_e32 v108, 16, v107
	v_and_b32_e32 v109, 0xffff0000, v107
	v_and_b32_e32 v107, 0xffff0000, v106
	v_lshlrev_b32_e32 v106, 16, v106
	v_pk_fma_f32 v[44:45], v[44:45], v[184:185], v[108:109]
	v_pk_fma_f32 v[42:43], v[42:43], v[182:183], v[106:107]
	s_nop 0
	v_cvt_pk_bf16_f32 v42, v42, v43
	v_cvt_pk_bf16_f32 v43, v44, v45
	global_store_dwordx2 v208, v[42:43], s[74:75] offset:64
	v_lshlrev_b32_e32 v112, 16, v111
	v_and_b32_e32 v113, 0xffff0000, v111
	v_and_b32_e32 v111, 0xffff0000, v110
	v_lshlrev_b32_e32 v110, 16, v110
	v_pk_fma_f32 v[48:49], v[48:49], v[188:189], v[112:113]
	v_pk_fma_f32 v[46:47], v[46:47], v[186:187], v[110:111]
	s_nop 0
	v_cvt_pk_bf16_f32 v46, v46, v47
	v_cvt_pk_bf16_f32 v47, v48, v49
	global_store_dwordx2 v208, v[46:47], s[74:75] offset:96
	v_lshlrev_b32_e32 v116, 16, v115
	v_and_b32_e32 v117, 0xffff0000, v115
	v_and_b32_e32 v115, 0xffff0000, v114
	v_lshlrev_b32_e32 v114, 16, v114
	v_pk_fma_f32 v[52:53], v[52:53], v[176:177], v[116:117]
	v_pk_fma_f32 v[50:51], v[50:51], v[174:175], v[114:115]
	s_nop 0
	v_cvt_pk_bf16_f32 v50, v50, v51
	v_cvt_pk_bf16_f32 v51, v52, v53
	global_store_dwordx2 v209, v[50:51], s[74:75] offset:0
	v_lshlrev_b32_e32 v120, 16, v119
	v_and_b32_e32 v121, 0xffff0000, v119
	v_and_b32_e32 v119, 0xffff0000, v118
	v_lshlrev_b32_e32 v118, 16, v118
	v_pk_fma_f32 v[56:57], v[56:57], v[180:181], v[120:121]
	v_pk_fma_f32 v[54:55], v[54:55], v[178:179], v[118:119]
	s_nop 0
	v_cvt_pk_bf16_f32 v54, v54, v55
	v_cvt_pk_bf16_f32 v55, v56, v57
	global_store_dwordx2 v209, v[54:55], s[74:75] offset:32
	v_lshlrev_b32_e32 v124, 16, v123
	v_and_b32_e32 v125, 0xffff0000, v123
	v_and_b32_e32 v123, 0xffff0000, v122
	v_lshlrev_b32_e32 v122, 16, v122
	v_pk_fma_f32 v[60:61], v[60:61], v[184:185], v[124:125]
	v_pk_fma_f32 v[58:59], v[58:59], v[182:183], v[122:123]
	s_nop 0
	v_cvt_pk_bf16_f32 v58, v58, v59
	v_cvt_pk_bf16_f32 v59, v60, v61
	global_store_dwordx2 v209, v[58:59], s[74:75] offset:64
	v_lshlrev_b32_e32 v128, 16, v127
	v_and_b32_e32 v129, 0xffff0000, v127
	v_and_b32_e32 v127, 0xffff0000, v126
	v_lshlrev_b32_e32 v126, 16, v126
	v_pk_fma_f32 v[64:65], v[64:65], v[188:189], v[128:129]
	v_pk_fma_f32 v[62:63], v[62:63], v[186:187], v[126:127]
	s_nop 0
	v_cvt_pk_bf16_f32 v62, v62, v63
	v_cvt_pk_bf16_f32 v63, v64, v65
	global_store_dwordx2 v209, v[62:63], s[74:75] offset:96
	s_add_u32 s78, s78, s79
	s_cmp_gt_u32 s78, 31
	s_cbranch_scc1 .Ldn_exit
	s_barrier
	s_branch .Ldn_tile
.Ldn_exit:
	v_mov_b32_e32 v163, 0
	v_mov_b32_e32 v164, 0x358637bd
	v_mov_b32_e32 v165, 1
	v_mov_b32_e32 v168, 0x2bf
	v_mov_b32_e32 v169, 0
	v_mov_b32_e32 v170, 0x340
	v_mov_b32_e32 v171, 0
	v_mov_b32_e32 v172, 0x33f
	v_mov_b32_e32 v173, 0
	v_mov_b32_e32 v202, 0xc00
	v_mov_b32_e32 v203, 0x7ffffc00
	v_mov_b32_e32 v204, 0xffffff00
	v_mov_b32_e32 v205, 0x400
	v_mov_b32_e32 v206, 0x100
	v_mov_b32_e32 v207, 0x3ff
	v_mov_b32_e32 v208, 0xff
	v_mov_b32_e32 v209, 0xcf
	v_mov_b32_e32 v210, 0xdf
	v_mov_b32_e32 v211, 0xef
	v_mbcnt_lo_u32_b32 v194, -1, 0
	v_mbcnt_hi_u32_b32 v194, -1, v194
	v_and_b32_e32 v195, 64, v194
	v_add_u32_e32 v195, 64, v195
	v_xor_b32_e32 v196, 32, v194
	v_xor_b32_e32 v197, 16, v194
	v_xor_b32_e32 v198, 8, v194
	v_xor_b32_e32 v199, 4, v194
	v_xor_b32_e32 v200, 2, v194
	v_xor_b32_e32 v201, 1, v194
	s_branch .LBB0_56
.LBB0_56:
	s_waitcnt lgkmcnt(0)
	s_barrier
	s_mov_b64 s[0:1], -1

.LBB0_207:
	s_andn2_b64 vcc, exec, s[2:3]
	s_cbranch_vccnz .LBB0_313
	s_waitcnt vmcnt(0) lgkmcnt(0)
	v_readlane_b32 s2, v253, 0
	v_readlane_b32 s3, v254, 4
	v_readlane_b32 s30, v252, 0
	v_readlane_b32 s31, v252, 1
	v_readlane_b32 s24, v252, 2
	v_readlane_b32 s25, v252, 3
	v_readlane_b32 s82, v252, 8
	v_readlane_b32 s80, v254, 52
	v_readlane_b32 s81, v254, 53
	s_mov_b32 s18, s10
	s_mov_b32 s19, s11
	s_and_b32 s77, s2, 7
	s_lshl_b32 s77, s77, 2
	s_lshr_b32 s78, s2, 3
	s_lshr_b32 s79, s3, 3
	s_cmp_gt_u32 s78, 31
	s_cbranch_scc1 .LBB0_312
	v_and_b32_e32 v170, 15, v1
	v_bfe_u32 v171, v1, 4, 2
	v_bfe_u32 v172, v1, 6, 1
	v_lshrrev_b32_e32 v173, 7, v1
	v_and_b32_e32 v162, 7, v170
	v_xor_b32_e32 v162, v162, v171
	v_lshlrev_b32_e32 v162, 4, v162
	v_lshlrev_b32_e32 v200, 13, v173
	v_lshl_add_u32 v200, v170, 7, v200
	v_add_u32_e32 v200, v200, v162
	v_xor_b32_e32 v201, 64, v200
	v_lshlrev_b32_e32 v202, 13, v172
	v_lshl_add_u32 v202, v170, 7, v202
	v_add_u32_e32 v202, v202, v162
	v_add_u32_e32 v202, 0x8000, v202
	v_xor_b32_e32 v203, 64, v202
	v_lshl_add_u32 v162, v173, 6, v170
	v_lshlrev_b32_e32 v172, 6, v172
	v_lshl_add_u32 v172, v171, 2, v172
	v_lshlrev_b32_e32 v190, 2, v172
	v_lshlrev_b32_e32 v206, 11, v162
	v_lshl_add_u32 v206, v172, 1, v206
	v_add_u32_e32 v207, 0x8000, v206
	v_add_u32_e32 v208, 0x10000, v206
	v_add_u32_e32 v209, 0x18000, v206
	v_lshlrev_b32_e32 v210, 12, v162
	v_add_u32_e32 v210, v210, v190
	v_add_u32_e32 v211, 0x10000, v210
	v_add_u32_e32 v168, 0x20000, v210
	v_add_u32_e32 v169, 0x30000, v210
	v_lshrrev_b32_e32 v170, 3, v1
	v_and_b32_e32 v171, 7, v1
	v_and_b32_e32 v173, 7, v170
	v_xor_b32_e32 v171, v171, v173
	v_lshlrev_b32_e32 v171, 4, v171
	v_mul_u32_u24_e32 v196, 0x800, v170
	v_add_u32_e32 v196, v196, v171
	v_add_u32_e32 v197, 0x20000, v196
	v_add_u32_e32 v198, 0x40000, v196
	v_add_u32_e32 v199, 0x60000, v196
	v_lshrrev_b32_e32 v170, 6, v1
	v_lshlrev_b32_e32 v170, 10, v170
	s_nop 0
	v_readfirstlane_b32 s76, v170
.Lop_tile:
	s_and_b32 s0, s78, 3
	s_or_b32 s0, s0, s77
	s_lshr_b32 s1, s78, 2
	s_lshl_b32 s1, s1, 7
	s_lshl_b32 s2, s0, 8
	s_mul_i32 s3, s2, 0x800
	s_add_u32 s68, s18, s3
	s_addc_u32 s69, s19, 0
	s_mul_i32 s3, s1, 0x800
	s_add_u32 s70, s80, s3
	s_addc_u32 s71, s81, 0
	s_lshl_b32 s3, s2, 11
	s_lshl_b32 s12, s1, 1
	s_add_u32 s3, s3, s12
	s_add_u32 s74, s24, s3
	s_addc_u32 s75, s25, 0
	s_add_i32 s12, s0, -12
	s_lshr_b32 s12, s12, 2
	s_cmp_lt_u32 s0, 16
	s_cselect_b32 s12, 0, s12
	s_cselect_b32 s14, s52, s54
	s_cselect_b32 s15, s53, s55
	s_mul_i32 s13, s82, 5
	s_add_i32 s12, s12, s13
	s_mul_i32 s12, s12, 0x6000
	s_add_u32 s12, s12, 0x2000
	s_lshl_b32 s13, s1, 2
	s_add_u32 s12, s12, s13
	s_add_u32 s72, s30, s12
	s_addc_u32 s73, s31, 0
	s_and_b32 s12, s0, 15
	s_lshl_b32 s12, s12, 20
	s_add_u32 s12, s12, s13
	s_add_u32 s14, s14, s12
	s_addc_u32 s15, s15, 0
	s_add_u32 m0, s76, 0x0
	s_nop 0
	global_load_lds_dwordx4 v196, s[68:69]
	s_add_u32 m0, s76, 0x2000
	s_nop 0
	global_load_lds_dwordx4 v197, s[68:69]
	s_add_u32 m0, s76, 0x4000
	s_nop 0
	global_load_lds_dwordx4 v198, s[68:69]
	s_add_u32 m0, s76, 0x6000
	s_nop 0
	global_load_lds_dwordx4 v199, s[68:69]
	s_add_u32 m0, s76, 0x8000
	s_nop 0
	global_load_lds_dwordx4 v196, s[70:71]
	s_add_u32 m0, s76, 0xa000
	s_nop 0
	global_load_lds_dwordx4 v197, s[70:71]
	s_add_u32 s68, s68, 0x80
	s_addc_u32 s69, s69, 0
	s_add_u32 s70, s70, 0x80
	s_addc_u32 s71, s71, 0
	s_add_u32 m0, s76, 0xc000
	s_nop 0
	global_load_lds_dwordx4 v196, s[68:69]
	s_add_u32 m0, s76, 0xe000
	s_nop 0
	global_load_lds_dwordx4 v197, s[68:69]
	s_add_u32 m0, s76, 0x10000
	s_nop 0
	global_load_lds_dwordx4 v198, s[68:69]
	s_add_u32 m0, s76, 0x12000
	s_nop 0
	global_load_lds_dwordx4 v199, s[68:69]
	s_add_u32 m0, s76, 0x14000
	s_nop 0
	global_load_lds_dwordx4 v196, s[70:71]
	s_add_u32 m0, s76, 0x16000
	s_nop 0
	global_load_lds_dwordx4 v197, s[70:71]
	s_add_u32 s68, s68, 0x80
	s_addc_u32 s69, s69, 0
	s_add_u32 s70, s70, 0x80
	s_addc_u32 s71, s71, 0
	global_load_dwordx4 v[174:177], v190, s[72:73] offset:0
	global_load_dwordx4 v[178:181], v190, s[72:73] offset:64
	global_load_dwordx4 v[182:185], v190, s[72:73] offset:128
	global_load_dwordx4 v[186:189], v190, s[72:73] offset:192
	s_cmp_lg_u32 s82, 0
	s_cbranch_scc1 .Lop_ldbf
	global_load_dwordx4 v[66:69], v210, s[14:15] offset:0
	global_load_dwordx4 v[70:73], v210, s[14:15] offset:64
	global_load_dwordx4 v[74:77], v210, s[14:15] offset:128
	global_load_dwordx4 v[78:81], v210, s[14:15] offset:192
	global_load_dwordx4 v[82:85], v211, s[14:15] offset:0
	global_load_dwordx4 v[86:89], v211, s[14:15] offset:64
	global_load_dwordx4 v[90:93], v211, s[14:15] offset:128
	global_load_dwordx4 v[94:97], v211, s[14:15] offset:192
	global_load_dwordx4 v[98:101], v168, s[14:15] offset:0
	global_load_dwordx4 v[102:105], v168, s[14:15] offset:64
	global_load_dwordx4 v[106:109], v168, s[14:15] offset:128
	global_load_dwordx4 v[110:113], v168, s[14:15] offset:192
	global_load_dwordx4 v[114:117], v169, s[14:15] offset:0
	global_load_dwordx4 v[118:121], v169, s[14:15] offset:64
	global_load_dwordx4 v[122:125], v169, s[14:15] offset:128
	global_load_dwordx4 v[126:129], v169, s[14:15] offset:192
	s_branch .Lop_lddone
.Lop_ldbf:
	global_load_dwordx2 v[66:67], v206, s[74:75] offset:0
	global_load_dwordx2 v[70:71], v206, s[74:75] offset:32
	global_load_dwordx2 v[74:75], v206, s[74:75] offset:64
	global_load_dwordx2 v[78:79], v206, s[74:75] offset:96
	global_load_dwordx2 v[82:83], v207, s[74:75] offset:0
	global_load_dwordx2 v[86:87], v207, s[74:75] offset:32
	global_load_dwordx2 v[90:91], v207, s[74:75] offset:64
	global_load_dwordx2 v[94:95], v207, s[74:75] offset:96
	global_load_dwordx2 v[98:99], v208, s[74:75] offset:0
	global_load_dwordx2 v[102:103], v208, s[74:75] offset:32
	global_load_dwordx2 v[106:107], v208, s[74:75] offset:64
	global_load_dwordx2 v[110:111], v208, s[74:75] offset:96
	global_load_dwordx2 v[114:115], v209, s[74:75] offset:0
	global_load_dwordx2 v[118:119], v209, s[74:75] offset:32
	global_load_dwordx2 v[122:123], v209, s[74:75] offset:64
	global_load_dwordx2 v[126:127], v209, s[74:75] offset:96
.Lop_lddone:
	s_waitcnt vmcnt(26)
	s_waitcnt lgkmcnt(0)
	s_barrier
	v_add_u32_e32 v204, 0x0, v200
	v_add_u32_e32 v205, 0x0, v202
	ds_read_b128 v[130:133], v204 offset:0
	ds_read_b128 v[134:137], v204 offset:2048
	ds_read_b128 v[138:141], v204 offset:4096
	ds_read_b128 v[142:145], v204 offset:6144
	ds_read_b128 v[146:149], v205 offset:0
	ds_read_b128 v[150:153], v205 offset:2048
	ds_read_b128 v[154:157], v205 offset:4096
	ds_read_b128 v[158:161], v205 offset:6144
	s_add_u32 m0, s76, 0x18000
	s_nop 0
	global_load_lds_dwordx4 v196, s[68:69]
	s_add_u32 m0, s76, 0x1a000
	s_nop 0
	global_load_lds_dwordx4 v197, s[68:69]
	s_add_u32 m0, s76, 0x1c000
	s_nop 0
	global_load_lds_dwordx4 v198, s[68:69]
	s_add_u32 m0, s76, 0x1e000
	s_nop 0
	global_load_lds_dwordx4 v199, s[68:69]
	s_add_u32 m0, s76, 0x20000
	s_nop 0
	global_load_lds_dwordx4 v196, s[70:71]
	s_add_u32 m0, s76, 0x22000
	s_nop 0
	global_load_lds_dwordx4 v197, s[70:71]
	s_add_u32 s68, s68, 0x80
	s_addc_u32 s69, s69, 0
	s_add_u32 s70, s70, 0x80
	s_addc_u32 s71, s71, 0
	s_waitcnt lgkmcnt(0)
	v_add_u32_e32 v204, 0x0, v201
	v_add_u32_e32 v205, 0x0, v203
	ds_read_b128 v[212:215], v204 offset:0
	ds_read_b128 v[216:219], v204 offset:2048
	ds_read_b128 v[220:223], v204 offset:4096
	ds_read_b128 v[224:227], v204 offset:6144
	ds_read_b128 v[228:231], v205 offset:0
	ds_read_b128 v[232:235], v205 offset:2048
	ds_read_b128 v[236:239], v205 offset:4096
	ds_read_b128 v[240:243], v205 offset:6144
	v_mfma_f32_16x16x32_bf16 v[2:5], v[146:149], v[130:133], 0
	v_mfma_f32_16x16x32_bf16 v[6:9], v[150:153], v[130:133], 0
	v_mfma_f32_16x16x32_bf16 v[10:13], v[154:157], v[130:133], 0
	v_mfma_f32_16x16x32_bf16 v[14:17], v[158:161], v[130:133], 0
	v_mfma_f32_16x16x32_bf16 v[18:21], v[146:149], v[134:137], 0
	v_mfma_f32_16x16x32_bf16 v[22:25], v[150:153], v[134:137], 0
	v_mfma_f32_16x16x32_bf16 v[26:29], v[154:157], v[134:137], 0
	v_mfma_f32_16x16x32_bf16 v[30:33], v[158:161], v[134:137], 0
	v_mfma_f32_16x16x32_bf16 v[34:37], v[146:149], v[138:141], 0
	v_mfma_f32_16x16x32_bf16 v[38:41], v[150:153], v[138:141], 0
	v_mfma_f32_16x16x32_bf16 v[42:45], v[154:157], v[138:141], 0
	v_mfma_f32_16x16x32_bf16 v[46:49], v[158:161], v[138:141], 0
	v_mfma_f32_16x16x32_bf16 v[50:53], v[146:149], v[142:145], 0
	v_mfma_f32_16x16x32_bf16 v[54:57], v[150:153], v[142:145], 0
	v_mfma_f32_16x16x32_bf16 v[58:61], v[154:157], v[142:145], 0
	v_mfma_f32_16x16x32_bf16 v[62:65], v[158:161], v[142:145], 0
	s_waitcnt vmcnt(26)
	s_waitcnt lgkmcnt(0)
	s_barrier
	v_add_u32_e32 v204, 0xc000, v200
	v_add_u32_e32 v205, 0xc000, v202
	ds_read_b128 v[130:133], v204 offset:0
	ds_read_b128 v[134:137], v204 offset:2048
	ds_read_b128 v[138:141], v204 offset:4096
	ds_read_b128 v[142:145], v204 offset:6144
	ds_read_b128 v[146:149], v205 offset:0
	ds_read_b128 v[150:153], v205 offset:2048
	ds_read_b128 v[154:157], v205 offset:4096
	ds_read_b128 v[158:161], v205 offset:6144
	v_mfma_f32_16x16x32_bf16 v[2:5], v[228:231], v[212:215], v[2:5]
	v_mfma_f32_16x16x32_bf16 v[6:9], v[232:235], v[212:215], v[6:9]
	s_add_u32 m0, s76, 0x0
	s_nop 0
	global_load_lds_dwordx4 v196, s[68:69]
	v_mfma_f32_16x16x32_bf16 v[10:13], v[236:239], v[212:215], v[10:13]
	v_mfma_f32_16x16x32_bf16 v[14:17], v[240:243], v[212:215], v[14:17]
	s_add_u32 m0, s76, 0x2000
	s_nop 0
	global_load_lds_dwordx4 v197, s[68:69]
	v_mfma_f32_16x16x32_bf16 v[18:21], v[228:231], v[216:219], v[18:21]
	v_mfma_f32_16x16x32_bf16 v[22:25], v[232:235], v[216:219], v[22:25]
	s_add_u32 m0, s76, 0x4000
	s_nop 0
	global_load_lds_dwordx4 v198, s[68:69]
	v_mfma_f32_16x16x32_bf16 v[26:29], v[236:239], v[216:219], v[26:29]
	v_mfma_f32_16x16x32_bf16 v[30:33], v[240:243], v[216:219], v[30:33]
	s_add_u32 m0, s76, 0x6000
	s_nop 0
	global_load_lds_dwordx4 v199, s[68:69]
	v_mfma_f32_16x16x32_bf16 v[34:37], v[228:231], v[220:223], v[34:37]
	v_mfma_f32_16x16x32_bf16 v[38:41], v[232:235], v[220:223], v[38:41]
	s_add_u32 m0, s76, 0x8000
	s_nop 0
	global_load_lds_dwordx4 v196, s[70:71]
	v_mfma_f32_16x16x32_bf16 v[42:45], v[236:239], v[220:223], v[42:45]
	v_mfma_f32_16x16x32_bf16 v[46:49], v[240:243], v[220:223], v[46:49]
	s_add_u32 m0, s76, 0xa000
	s_nop 0
	global_load_lds_dwordx4 v197, s[70:71]
	v_mfma_f32_16x16x32_bf16 v[50:53], v[228:231], v[224:227], v[50:53]
	v_mfma_f32_16x16x32_bf16 v[54:57], v[232:235], v[224:227], v[54:57]
	s_add_u32 s68, s68, 0x80
	s_addc_u32 s69, s69, 0
	s_add_u32 s70, s70, 0x80
	s_addc_u32 s71, s71, 0
	v_mfma_f32_16x16x32_bf16 v[58:61], v[236:239], v[224:227], v[58:61]
	v_mfma_f32_16x16x32_bf16 v[62:65], v[240:243], v[224:227], v[62:65]
	s_waitcnt lgkmcnt(0)
	v_add_u32_e32 v204, 0xc000, v201
	v_add_u32_e32 v205, 0xc000, v203
	ds_read_b128 v[212:215], v204 offset:0
	ds_read_b128 v[216:219], v204 offset:2048
	ds_read_b128 v[220:223], v204 offset:4096
	ds_read_b128 v[224:227], v204 offset:6144
	ds_read_b128 v[228:231], v205 offset:0
	ds_read_b128 v[232:235], v205 offset:2048
	ds_read_b128 v[236:239], v205 offset:4096
	ds_read_b128 v[240:243], v205 offset:6144
	v_mfma_f32_16x16x32_bf16 v[2:5], v[146:149], v[130:133], v[2:5]
	v_mfma_f32_16x16x32_bf16 v[6:9], v[150:153], v[130:133], v[6:9]
	v_mfma_f32_16x16x32_bf16 v[10:13], v[154:157], v[130:133], v[10:13]
	v_mfma_f32_16x16x32_bf16 v[14:17], v[158:161], v[130:133], v[14:17]
	v_mfma_f32_16x16x32_bf16 v[18:21], v[146:149], v[134:137], v[18:21]
	v_mfma_f32_16x16x32_bf16 v[22:25], v[150:153], v[134:137], v[22:25]
	v_mfma_f32_16x16x32_bf16 v[26:29], v[154:157], v[134:137], v[26:29]
	v_mfma_f32_16x16x32_bf16 v[30:33], v[158:161], v[134:137], v[30:33]
	v_mfma_f32_16x16x32_bf16 v[34:37], v[146:149], v[138:141], v[34:37]
	v_mfma_f32_16x16x32_bf16 v[38:41], v[150:153], v[138:141], v[38:41]
	v_mfma_f32_16x16x32_bf16 v[42:45], v[154:157], v[138:141], v[42:45]
	v_mfma_f32_16x16x32_bf16 v[46:49], v[158:161], v[138:141], v[46:49]
	v_mfma_f32_16x16x32_bf16 v[50:53], v[146:149], v[142:145], v[50:53]
	v_mfma_f32_16x16x32_bf16 v[54:57], v[150:153], v[142:145], v[54:57]
	v_mfma_f32_16x16x32_bf16 v[58:61], v[154:157], v[142:145], v[58:61]
	v_mfma_f32_16x16x32_bf16 v[62:65], v[158:161], v[142:145], v[62:65]
	s_mov_b32 s16, 4
.Lop_kloop:
	s_waitcnt vmcnt(6)
	s_waitcnt lgkmcnt(0)
	s_barrier
	v_add_u32_e32 v204, 0x18000, v200
	v_add_u32_e32 v205, 0x18000, v202
	ds_read_b128 v[130:133], v204 offset:0
	ds_read_b128 v[134:137], v204 offset:2048
	ds_read_b128 v[138:141], v204 offset:4096
	ds_read_b128 v[142:145], v204 offset:6144
	ds_read_b128 v[146:149], v205 offset:0
	ds_read_b128 v[150:153], v205 offset:2048
	ds_read_b128 v[154:157], v205 offset:4096
	ds_read_b128 v[158:161], v205 offset:6144
	v_mfma_f32_16x16x32_bf16 v[2:5], v[228:231], v[212:215], v[2:5]
	v_mfma_f32_16x16x32_bf16 v[6:9], v[232:235], v[212:215], v[6:9]
	s_add_u32 m0, s76, 0xc000
	s_nop 0
	global_load_lds_dwordx4 v196, s[68:69]
	v_mfma_f32_16x16x32_bf16 v[10:13], v[236:239], v[212:215], v[10:13]
	v_mfma_f32_16x16x32_bf16 v[14:17], v[240:243], v[212:215], v[14:17]
	s_add_u32 m0, s76, 0xe000
	s_nop 0
	global_load_lds_dwordx4 v197, s[68:69]
	v_mfma_f32_16x16x32_bf16 v[18:21], v[228:231], v[216:219], v[18:21]
	v_mfma_f32_16x16x32_bf16 v[22:25], v[232:235], v[216:219], v[22:25]
	s_add_u32 m0, s76, 0x10000
	s_nop 0
	global_load_lds_dwordx4 v198, s[68:69]
	v_mfma_f32_16x16x32_bf16 v[26:29], v[236:239], v[216:219], v[26:29]
	v_mfma_f32_16x16x32_bf16 v[30:33], v[240:243], v[216:219], v[30:33]
	s_add_u32 m0, s76, 0x12000
	s_nop 0
	global_load_lds_dwordx4 v199, s[68:69]
	v_mfma_f32_16x16x32_bf16 v[34:37], v[228:231], v[220:223], v[34:37]
	v_mfma_f32_16x16x32_bf16 v[38:41], v[232:235], v[220:223], v[38:41]
	s_add_u32 m0, s76, 0x14000
	s_nop 0
	global_load_lds_dwordx4 v196, s[70:71]
	v_mfma_f32_16x16x32_bf16 v[42:45], v[236:239], v[220:223], v[42:45]
	v_mfma_f32_16x16x32_bf16 v[46:49], v[240:243], v[220:223], v[46:49]
	s_add_u32 m0, s76, 0x16000
	s_nop 0
	global_load_lds_dwordx4 v197, s[70:71]
	v_mfma_f32_16x16x32_bf16 v[50:53], v[228:231], v[224:227], v[50:53]
	v_mfma_f32_16x16x32_bf16 v[54:57], v[232:235], v[224:227], v[54:57]
	s_add_u32 s68, s68, 0x80
	s_addc_u32 s69, s69, 0
	s_add_u32 s70, s70, 0x80
	s_addc_u32 s71, s71, 0
	v_mfma_f32_16x16x32_bf16 v[58:61], v[236:239], v[224:227], v[58:61]
	v_mfma_f32_16x16x32_bf16 v[62:65], v[240:243], v[224:227], v[62:65]
	s_waitcnt lgkmcnt(0)
	v_add_u32_e32 v204, 0x18000, v201
	v_add_u32_e32 v205, 0x18000, v203
	ds_read_b128 v[212:215], v204 offset:0
	ds_read_b128 v[216:219], v204 offset:2048
	ds_read_b128 v[220:223], v204 offset:4096
	ds_read_b128 v[224:227], v204 offset:6144
	ds_read_b128 v[228:231], v205 offset:0
	ds_read_b128 v[232:235], v205 offset:2048
	ds_read_b128 v[236:239], v205 offset:4096
	ds_read_b128 v[240:243], v205 offset:6144
	v_mfma_f32_16x16x32_bf16 v[2:5], v[146:149], v[130:133], v[2:5]
	v_mfma_f32_16x16x32_bf16 v[6:9], v[150:153], v[130:133], v[6:9]
	v_mfma_f32_16x16x32_bf16 v[10:13], v[154:157], v[130:133], v[10:13]
	v_mfma_f32_16x16x32_bf16 v[14:17], v[158:161], v[130:133], v[14:17]
	v_mfma_f32_16x16x32_bf16 v[18:21], v[146:149], v[134:137], v[18:21]
	v_mfma_f32_16x16x32_bf16 v[22:25], v[150:153], v[134:137], v[22:25]
	v_mfma_f32_16x16x32_bf16 v[26:29], v[154:157], v[134:137], v[26:29]
	v_mfma_f32_16x16x32_bf16 v[30:33], v[158:161], v[134:137], v[30:33]
	v_mfma_f32_16x16x32_bf16 v[34:37], v[146:149], v[138:141], v[34:37]
	v_mfma_f32_16x16x32_bf16 v[38:41], v[150:153], v[138:141], v[38:41]
	v_mfma_f32_16x16x32_bf16 v[42:45], v[154:157], v[138:141], v[42:45]
	v_mfma_f32_16x16x32_bf16 v[46:49], v[158:161], v[138:141], v[46:49]
	v_mfma_f32_16x16x32_bf16 v[50:53], v[146:149], v[142:145], v[50:53]
	v_mfma_f32_16x16x32_bf16 v[54:57], v[150:153], v[142:145], v[54:57]
	v_mfma_f32_16x16x32_bf16 v[58:61], v[154:157], v[142:145], v[58:61]
	v_mfma_f32_16x16x32_bf16 v[62:65], v[158:161], v[142:145], v[62:65]
	s_waitcnt vmcnt(6)
	s_waitcnt lgkmcnt(0)
	s_barrier
	v_add_u32_e32 v204, 0x0, v200
	v_add_u32_e32 v205, 0x0, v202
	ds_read_b128 v[130:133], v204 offset:0
	ds_read_b128 v[134:137], v204 offset:2048
	ds_read_b128 v[138:141], v204 offset:4096
	ds_read_b128 v[142:145], v204 offset:6144
	ds_read_b128 v[146:149], v205 offset:0
	ds_read_b128 v[150:153], v205 offset:2048
	ds_read_b128 v[154:157], v205 offset:4096
	ds_read_b128 v[158:161], v205 offset:6144
	v_mfma_f32_16x16x32_bf16 v[2:5], v[228:231], v[212:215], v[2:5]
	v_mfma_f32_16x16x32_bf16 v[6:9], v[232:235], v[212:215], v[6:9]
	s_add_u32 m0, s76, 0x18000
	s_nop 0
	global_load_lds_dwordx4 v196, s[68:69]
	v_mfma_f32_16x16x32_bf16 v[10:13], v[236:239], v[212:215], v[10:13]
	v_mfma_f32_16x16x32_bf16 v[14:17], v[240:243], v[212:215], v[14:17]
	s_add_u32 m0, s76, 0x1a000
	s_nop 0
	global_load_lds_dwordx4 v197, s[68:69]
	v_mfma_f32_16x16x32_bf16 v[18:21], v[228:231], v[216:219], v[18:21]
	v_mfma_f32_16x16x32_bf16 v[22:25], v[232:235], v[216:219], v[22:25]
	s_add_u32 m0, s76, 0x1c000
	s_nop 0
	global_load_lds_dwordx4 v198, s[68:69]
	v_mfma_f32_16x16x32_bf16 v[26:29], v[236:239], v[216:219], v[26:29]
	v_mfma_f32_16x16x32_bf16 v[30:33], v[240:243], v[216:219], v[30:33]
	s_add_u32 m0, s76, 0x1e000
	s_nop 0
	global_load_lds_dwordx4 v199, s[68:69]
	v_mfma_f32_16x16x32_bf16 v[34:37], v[228:231], v[220:223], v[34:37]
	v_mfma_f32_16x16x32_bf16 v[38:41], v[232:235], v[220:223], v[38:41]
	s_add_u32 m0, s76, 0x20000
	s_nop 0
	global_load_lds_dwordx4 v196, s[70:71]
	v_mfma_f32_16x16x32_bf16 v[42:45], v[236:239], v[220:223], v[42:45]
	v_mfma_f32_16x16x32_bf16 v[46:49], v[240:243], v[220:223], v[46:49]
	s_add_u32 m0, s76, 0x22000
	s_nop 0
	global_load_lds_dwordx4 v197, s[70:71]
	v_mfma_f32_16x16x32_bf16 v[50:53], v[228:231], v[224:227], v[50:53]
	v_mfma_f32_16x16x32_bf16 v[54:57], v[232:235], v[224:227], v[54:57]
	s_add_u32 s68, s68, 0x80
	s_addc_u32 s69, s69, 0
	s_add_u32 s70, s70, 0x80
	s_addc_u32 s71, s71, 0
	v_mfma_f32_16x16x32_bf16 v[58:61], v[236:239], v[224:227], v[58:61]
	v_mfma_f32_16x16x32_bf16 v[62:65], v[240:243], v[224:227], v[62:65]
	s_waitcnt lgkmcnt(0)
	v_add_u32_e32 v204, 0x0, v201
	v_add_u32_e32 v205, 0x0, v203
	ds_read_b128 v[212:215], v204 offset:0
	ds_read_b128 v[216:219], v204 offset:2048
	ds_read_b128 v[220:223], v204 offset:4096
	ds_read_b128 v[224:227], v204 offset:6144
	ds_read_b128 v[228:231], v205 offset:0
	ds_read_b128 v[232:235], v205 offset:2048
	ds_read_b128 v[236:239], v205 offset:4096
	ds_read_b128 v[240:243], v205 offset:6144
	v_mfma_f32_16x16x32_bf16 v[2:5], v[146:149], v[130:133], v[2:5]
	v_mfma_f32_16x16x32_bf16 v[6:9], v[150:153], v[130:133], v[6:9]
	v_mfma_f32_16x16x32_bf16 v[10:13], v[154:157], v[130:133], v[10:13]
	v_mfma_f32_16x16x32_bf16 v[14:17], v[158:161], v[130:133], v[14:17]
	v_mfma_f32_16x16x32_bf16 v[18:21], v[146:149], v[134:137], v[18:21]
	v_mfma_f32_16x16x32_bf16 v[22:25], v[150:153], v[134:137], v[22:25]
	v_mfma_f32_16x16x32_bf16 v[26:29], v[154:157], v[134:137], v[26:29]
	v_mfma_f32_16x16x32_bf16 v[30:33], v[158:161], v[134:137], v[30:33]
	v_mfma_f32_16x16x32_bf16 v[34:37], v[146:149], v[138:141], v[34:37]
	v_mfma_f32_16x16x32_bf16 v[38:41], v[150:153], v[138:141], v[38:41]
	v_mfma_f32_16x16x32_bf16 v[42:45], v[154:157], v[138:141], v[42:45]
	v_mfma_f32_16x16x32_bf16 v[46:49], v[158:161], v[138:141], v[46:49]
	v_mfma_f32_16x16x32_bf16 v[50:53], v[146:149], v[142:145], v[50:53]
	v_mfma_f32_16x16x32_bf16 v[54:57], v[150:153], v[142:145], v[54:57]
	v_mfma_f32_16x16x32_bf16 v[58:61], v[154:157], v[142:145], v[58:61]
	v_mfma_f32_16x16x32_bf16 v[62:65], v[158:161], v[142:145], v[62:65]
	s_waitcnt vmcnt(6)
	s_waitcnt lgkmcnt(0)
	s_barrier
	v_add_u32_e32 v204, 0xc000, v200
	v_add_u32_e32 v205, 0xc000, v202
	ds_read_b128 v[130:133], v204 offset:0
	ds_read_b128 v[134:137], v204 offset:2048
	ds_read_b128 v[138:141], v204 offset:4096
	ds_read_b128 v[142:145], v204 offset:6144
	ds_read_b128 v[146:149], v205 offset:0
	ds_read_b128 v[150:153], v205 offset:2048
	ds_read_b128 v[154:157], v205 offset:4096
	ds_read_b128 v[158:161], v205 offset:6144
	v_mfma_f32_16x16x32_bf16 v[2:5], v[228:231], v[212:215], v[2:5]
	v_mfma_f32_16x16x32_bf16 v[6:9], v[232:235], v[212:215], v[6:9]
	s_add_u32 m0, s76, 0x0
	s_nop 0
	global_load_lds_dwordx4 v196, s[68:69]
	v_mfma_f32_16x16x32_bf16 v[10:13], v[236:239], v[212:215], v[10:13]
	v_mfma_f32_16x16x32_bf16 v[14:17], v[240:243], v[212:215], v[14:17]
	s_add_u32 m0, s76, 0x2000
	s_nop 0
	global_load_lds_dwordx4 v197, s[68:69]
	v_mfma_f32_16x16x32_bf16 v[18:21], v[228:231], v[216:219], v[18:21]
	v_mfma_f32_16x16x32_bf16 v[22:25], v[232:235], v[216:219], v[22:25]
	s_add_u32 m0, s76, 0x4000
	s_nop 0
	global_load_lds_dwordx4 v198, s[68:69]
	v_mfma_f32_16x16x32_bf16 v[26:29], v[236:239], v[216:219], v[26:29]
	v_mfma_f32_16x16x32_bf16 v[30:33], v[240:243], v[216:219], v[30:33]
	s_add_u32 m0, s76, 0x6000
	s_nop 0
	global_load_lds_dwordx4 v199, s[68:69]
	v_mfma_f32_16x16x32_bf16 v[34:37], v[228:231], v[220:223], v[34:37]
	v_mfma_f32_16x16x32_bf16 v[38:41], v[232:235], v[220:223], v[38:41]
	s_add_u32 m0, s76, 0x8000
	s_nop 0
	global_load_lds_dwordx4 v196, s[70:71]
	v_mfma_f32_16x16x32_bf16 v[42:45], v[236:239], v[220:223], v[42:45]
	v_mfma_f32_16x16x32_bf16 v[46:49], v[240:243], v[220:223], v[46:49]
	s_add_u32 m0, s76, 0xa000
	s_nop 0
	global_load_lds_dwordx4 v197, s[70:71]
	v_mfma_f32_16x16x32_bf16 v[50:53], v[228:231], v[224:227], v[50:53]
	v_mfma_f32_16x16x32_bf16 v[54:57], v[232:235], v[224:227], v[54:57]
	s_add_u32 s68, s68, 0x80
	s_addc_u32 s69, s69, 0
	s_add_u32 s70, s70, 0x80
	s_addc_u32 s71, s71, 0
	v_mfma_f32_16x16x32_bf16 v[58:61], v[236:239], v[224:227], v[58:61]
	v_mfma_f32_16x16x32_bf16 v[62:65], v[240:243], v[224:227], v[62:65]
	s_waitcnt lgkmcnt(0)
	v_add_u32_e32 v204, 0xc000, v201
	v_add_u32_e32 v205, 0xc000, v203
	ds_read_b128 v[212:215], v204 offset:0
	ds_read_b128 v[216:219], v204 offset:2048
	ds_read_b128 v[220:223], v204 offset:4096
	ds_read_b128 v[224:227], v204 offset:6144
	ds_read_b128 v[228:231], v205 offset:0
	ds_read_b128 v[232:235], v205 offset:2048
	ds_read_b128 v[236:239], v205 offset:4096
	ds_read_b128 v[240:243], v205 offset:6144
	v_mfma_f32_16x16x32_bf16 v[2:5], v[146:149], v[130:133], v[2:5]
	v_mfma_f32_16x16x32_bf16 v[6:9], v[150:153], v[130:133], v[6:9]
	v_mfma_f32_16x16x32_bf16 v[10:13], v[154:157], v[130:133], v[10:13]
	v_mfma_f32_16x16x32_bf16 v[14:17], v[158:161], v[130:133], v[14:17]
	v_mfma_f32_16x16x32_bf16 v[18:21], v[146:149], v[134:137], v[18:21]
	v_mfma_f32_16x16x32_bf16 v[22:25], v[150:153], v[134:137], v[22:25]
	v_mfma_f32_16x16x32_bf16 v[26:29], v[154:157], v[134:137], v[26:29]
	v_mfma_f32_16x16x32_bf16 v[30:33], v[158:161], v[134:137], v[30:33]
	v_mfma_f32_16x16x32_bf16 v[34:37], v[146:149], v[138:141], v[34:37]
	v_mfma_f32_16x16x32_bf16 v[38:41], v[150:153], v[138:141], v[38:41]
	v_mfma_f32_16x16x32_bf16 v[42:45], v[154:157], v[138:141], v[42:45]
	v_mfma_f32_16x16x32_bf16 v[46:49], v[158:161], v[138:141], v[46:49]
	v_mfma_f32_16x16x32_bf16 v[50:53], v[146:149], v[142:145], v[50:53]
	v_mfma_f32_16x16x32_bf16 v[54:57], v[150:153], v[142:145], v[54:57]
	v_mfma_f32_16x16x32_bf16 v[58:61], v[154:157], v[142:145], v[58:61]
	v_mfma_f32_16x16x32_bf16 v[62:65], v[158:161], v[142:145], v[62:65]
	s_add_i32 s16, s16, -1
	s_cmp_lg_u32 s16, 0
	s_cbranch_scc1 .Lop_kloop
	s_waitcnt vmcnt(6)
	s_waitcnt lgkmcnt(0)
	s_barrier
	v_add_u32_e32 v204, 0x18000, v200
	v_add_u32_e32 v205, 0x18000, v202
	ds_read_b128 v[130:133], v204 offset:0
	ds_read_b128 v[134:137], v204 offset:2048
	ds_read_b128 v[138:141], v204 offset:4096
	ds_read_b128 v[142:145], v204 offset:6144
	ds_read_b128 v[146:149], v205 offset:0
	ds_read_b128 v[150:153], v205 offset:2048
	ds_read_b128 v[154:157], v205 offset:4096
	ds_read_b128 v[158:161], v205 offset:6144
	v_mfma_f32_16x16x32_bf16 v[2:5], v[228:231], v[212:215], v[2:5]
	v_mfma_f32_16x16x32_bf16 v[6:9], v[232:235], v[212:215], v[6:9]
	v_mfma_f32_16x16x32_bf16 v[10:13], v[236:239], v[212:215], v[10:13]
	v_mfma_f32_16x16x32_bf16 v[14:17], v[240:243], v[212:215], v[14:17]
	v_mfma_f32_16x16x32_bf16 v[18:21], v[228:231], v[216:219], v[18:21]
	v_mfma_f32_16x16x32_bf16 v[22:25], v[232:235], v[216:219], v[22:25]
	v_mfma_f32_16x16x32_bf16 v[26:29], v[236:239], v[216:219], v[26:29]
	v_mfma_f32_16x16x32_bf16 v[30:33], v[240:243], v[216:219], v[30:33]
	v_mfma_f32_16x16x32_bf16 v[34:37], v[228:231], v[220:223], v[34:37]
	v_mfma_f32_16x16x32_bf16 v[38:41], v[232:235], v[220:223], v[38:41]
	v_mfma_f32_16x16x32_bf16 v[42:45], v[236:239], v[220:223], v[42:45]
	v_mfma_f32_16x16x32_bf16 v[46:49], v[240:243], v[220:223], v[46:49]
	v_mfma_f32_16x16x32_bf16 v[50:53], v[228:231], v[224:227], v[50:53]
	v_mfma_f32_16x16x32_bf16 v[54:57], v[232:235], v[224:227], v[54:57]
	v_mfma_f32_16x16x32_bf16 v[58:61], v[236:239], v[224:227], v[58:61]
	v_mfma_f32_16x16x32_bf16 v[62:65], v[240:243], v[224:227], v[62:65]
	s_waitcnt lgkmcnt(0)
	v_add_u32_e32 v204, 0x18000, v201
	v_add_u32_e32 v205, 0x18000, v203
	ds_read_b128 v[212:215], v204 offset:0
	ds_read_b128 v[216:219], v204 offset:2048
	ds_read_b128 v[220:223], v204 offset:4096
	ds_read_b128 v[224:227], v204 offset:6144
	ds_read_b128 v[228:231], v205 offset:0
	ds_read_b128 v[232:235], v205 offset:2048
	ds_read_b128 v[236:239], v205 offset:4096
	ds_read_b128 v[240:243], v205 offset:6144
	v_mfma_f32_16x16x32_bf16 v[2:5], v[146:149], v[130:133], v[2:5]
	v_mfma_f32_16x16x32_bf16 v[6:9], v[150:153], v[130:133], v[6:9]
	v_mfma_f32_16x16x32_bf16 v[10:13], v[154:157], v[130:133], v[10:13]
	v_mfma_f32_16x16x32_bf16 v[14:17], v[158:161], v[130:133], v[14:17]
	v_mfma_f32_16x16x32_bf16 v[18:21], v[146:149], v[134:137], v[18:21]
	v_mfma_f32_16x16x32_bf16 v[22:25], v[150:153], v[134:137], v[22:25]
	v_mfma_f32_16x16x32_bf16 v[26:29], v[154:157], v[134:137], v[26:29]
	v_mfma_f32_16x16x32_bf16 v[30:33], v[158:161], v[134:137], v[30:33]
	v_mfma_f32_16x16x32_bf16 v[34:37], v[146:149], v[138:141], v[34:37]
	v_mfma_f32_16x16x32_bf16 v[38:41], v[150:153], v[138:141], v[38:41]
	v_mfma_f32_16x16x32_bf16 v[42:45], v[154:157], v[138:141], v[42:45]
	v_mfma_f32_16x16x32_bf16 v[46:49], v[158:161], v[138:141], v[46:49]
	v_mfma_f32_16x16x32_bf16 v[50:53], v[146:149], v[142:145], v[50:53]
	v_mfma_f32_16x16x32_bf16 v[54:57], v[150:153], v[142:145], v[54:57]
	v_mfma_f32_16x16x32_bf16 v[58:61], v[154:157], v[142:145], v[58:61]
	v_mfma_f32_16x16x32_bf16 v[62:65], v[158:161], v[142:145], v[62:65]
	s_waitcnt vmcnt(0)
	s_waitcnt lgkmcnt(0)
	s_barrier
	v_add_u32_e32 v204, 0x0, v200
	v_add_u32_e32 v205, 0x0, v202
	ds_read_b128 v[130:133], v204 offset:0
	ds_read_b128 v[134:137], v204 offset:2048
	ds_read_b128 v[138:141], v204 offset:4096
	ds_read_b128 v[142:145], v204 offset:6144
	ds_read_b128 v[146:149], v205 offset:0
	ds_read_b128 v[150:153], v205 offset:2048
	ds_read_b128 v[154:157], v205 offset:4096
	ds_read_b128 v[158:161], v205 offset:6144
	v_mfma_f32_16x16x32_bf16 v[2:5], v[228:231], v[212:215], v[2:5]
	v_mfma_f32_16x16x32_bf16 v[6:9], v[232:235], v[212:215], v[6:9]
	v_mfma_f32_16x16x32_bf16 v[10:13], v[236:239], v[212:215], v[10:13]
	v_mfma_f32_16x16x32_bf16 v[14:17], v[240:243], v[212:215], v[14:17]
	v_mfma_f32_16x16x32_bf16 v[18:21], v[228:231], v[216:219], v[18:21]
	v_mfma_f32_16x16x32_bf16 v[22:25], v[232:235], v[216:219], v[22:25]
	v_mfma_f32_16x16x32_bf16 v[26:29], v[236:239], v[216:219], v[26:29]
	v_mfma_f32_16x16x32_bf16 v[30:33], v[240:243], v[216:219], v[30:33]
	v_mfma_f32_16x16x32_bf16 v[34:37], v[228:231], v[220:223], v[34:37]
	v_mfma_f32_16x16x32_bf16 v[38:41], v[232:235], v[220:223], v[38:41]
	v_mfma_f32_16x16x32_bf16 v[42:45], v[236:239], v[220:223], v[42:45]
	v_mfma_f32_16x16x32_bf16 v[46:49], v[240:243], v[220:223], v[46:49]
	v_mfma_f32_16x16x32_bf16 v[50:53], v[228:231], v[224:227], v[50:53]
	v_mfma_f32_16x16x32_bf16 v[54:57], v[232:235], v[224:227], v[54:57]
	v_mfma_f32_16x16x32_bf16 v[58:61], v[236:239], v[224:227], v[58:61]
	v_mfma_f32_16x16x32_bf16 v[62:65], v[240:243], v[224:227], v[62:65]
	s_waitcnt lgkmcnt(0)
	v_add_u32_e32 v204, 0x0, v201
	v_add_u32_e32 v205, 0x0, v203
	ds_read_b128 v[212:215], v204 offset:0
	ds_read_b128 v[216:219], v204 offset:2048
	ds_read_b128 v[220:223], v204 offset:4096
	ds_read_b128 v[224:227], v204 offset:6144
	ds_read_b128 v[228:231], v205 offset:0
	ds_read_b128 v[232:235], v205 offset:2048
	ds_read_b128 v[236:239], v205 offset:4096
	ds_read_b128 v[240:243], v205 offset:6144
	v_mfma_f32_16x16x32_bf16 v[2:5], v[146:149], v[130:133], v[2:5]
	v_mfma_f32_16x16x32_bf16 v[6:9], v[150:153], v[130:133], v[6:9]
	v_mfma_f32_16x16x32_bf16 v[10:13], v[154:157], v[130:133], v[10:13]
	v_mfma_f32_16x16x32_bf16 v[14:17], v[158:161], v[130:133], v[14:17]
	v_mfma_f32_16x16x32_bf16 v[18:21], v[146:149], v[134:137], v[18:21]
	v_mfma_f32_16x16x32_bf16 v[22:25], v[150:153], v[134:137], v[22:25]
	v_mfma_f32_16x16x32_bf16 v[26:29], v[154:157], v[134:137], v[26:29]
	v_mfma_f32_16x16x32_bf16 v[30:33], v[158:161], v[134:137], v[30:33]
	v_mfma_f32_16x16x32_bf16 v[34:37], v[146:149], v[138:141], v[34:37]
	v_mfma_f32_16x16x32_bf16 v[38:41], v[150:153], v[138:141], v[38:41]
	v_mfma_f32_16x16x32_bf16 v[42:45], v[154:157], v[138:141], v[42:45]
	v_mfma_f32_16x16x32_bf16 v[46:49], v[158:161], v[138:141], v[46:49]
	v_mfma_f32_16x16x32_bf16 v[50:53], v[146:149], v[142:145], v[50:53]
	v_mfma_f32_16x16x32_bf16 v[54:57], v[150:153], v[142:145], v[54:57]
	v_mfma_f32_16x16x32_bf16 v[58:61], v[154:157], v[142:145], v[58:61]
	v_mfma_f32_16x16x32_bf16 v[62:65], v[158:161], v[142:145], v[62:65]
	s_waitcnt lgkmcnt(0)
	v_mfma_f32_16x16x32_bf16 v[2:5], v[228:231], v[212:215], v[2:5]
	v_mfma_f32_16x16x32_bf16 v[6:9], v[232:235], v[212:215], v[6:9]
	v_mfma_f32_16x16x32_bf16 v[10:13], v[236:239], v[212:215], v[10:13]
	v_mfma_f32_16x16x32_bf16 v[14:17], v[240:243], v[212:215], v[14:17]
	v_mfma_f32_16x16x32_bf16 v[18:21], v[228:231], v[216:219], v[18:21]
	v_mfma_f32_16x16x32_bf16 v[22:25], v[232:235], v[216:219], v[22:25]
	v_mfma_f32_16x16x32_bf16 v[26:29], v[236:239], v[216:219], v[26:29]
	v_mfma_f32_16x16x32_bf16 v[30:33], v[240:243], v[216:219], v[30:33]
	v_mfma_f32_16x16x32_bf16 v[34:37], v[228:231], v[220:223], v[34:37]
	v_mfma_f32_16x16x32_bf16 v[38:41], v[232:235], v[220:223], v[38:41]
	v_mfma_f32_16x16x32_bf16 v[42:45], v[236:239], v[220:223], v[42:45]
	v_mfma_f32_16x16x32_bf16 v[46:49], v[240:243], v[220:223], v[46:49]
	v_mfma_f32_16x16x32_bf16 v[50:53], v[228:231], v[224:227], v[50:53]
	v_mfma_f32_16x16x32_bf16 v[54:57], v[232:235], v[224:227], v[54:57]
	v_mfma_f32_16x16x32_bf16 v[58:61], v[236:239], v[224:227], v[58:61]
	v_mfma_f32_16x16x32_bf16 v[62:65], v[240:243], v[224:227], v[62:65]
	s_waitcnt vmcnt(0)
	s_nop 7
	s_cmp_lg_u32 s82, 0
	s_cbranch_scc1 .Lop_cvbf
	v_pk_fma_f32 v[4:5], v[4:5], v[176:177], v[68:69]
	v_pk_fma_f32 v[2:3], v[2:3], v[174:175], v[66:67]
	s_nop 0
	v_cvt_pk_bf16_f32 v2, v2, v3
	v_cvt_pk_bf16_f32 v3, v4, v5
	global_store_dwordx2 v206, v[2:3], s[74:75] offset:0
	v_pk_fma_f32 v[8:9], v[8:9], v[180:181], v[72:73]
	v_pk_fma_f32 v[6:7], v[6:7], v[178:179], v[70:71]
	s_nop 0
	v_cvt_pk_bf16_f32 v6, v6, v7
	v_cvt_pk_bf16_f32 v7, v8, v9
	global_store_dwordx2 v206, v[6:7], s[74:75] offset:32
	v_pk_fma_f32 v[12:13], v[12:13], v[184:185], v[76:77]
	v_pk_fma_f32 v[10:11], v[10:11], v[182:183], v[74:75]
	s_nop 0
	v_cvt_pk_bf16_f32 v10, v10, v11
	v_cvt_pk_bf16_f32 v11, v12, v13
	global_store_dwordx2 v206, v[10:11], s[74:75] offset:64
	v_pk_fma_f32 v[16:17], v[16:17], v[188:189], v[80:81]
	v_pk_fma_f32 v[14:15], v[14:15], v[186:187], v[78:79]
	s_nop 0
	v_cvt_pk_bf16_f32 v14, v14, v15
	v_cvt_pk_bf16_f32 v15, v16, v17
	global_store_dwordx2 v206, v[14:15], s[74:75] offset:96
	v_pk_fma_f32 v[20:21], v[20:21], v[176:177], v[84:85]
	v_pk_fma_f32 v[18:19], v[18:19], v[174:175], v[82:83]
	s_nop 0
	v_cvt_pk_bf16_f32 v18, v18, v19
	v_cvt_pk_bf16_f32 v19, v20, v21
	global_store_dwordx2 v207, v[18:19], s[74:75] offset:0
	v_pk_fma_f32 v[24:25], v[24:25], v[180:181], v[88:89]
	v_pk_fma_f32 v[22:23], v[22:23], v[178:179], v[86:87]
	s_nop 0
	v_cvt_pk_bf16_f32 v22, v22, v23
	v_cvt_pk_bf16_f32 v23, v24, v25
	global_store_dwordx2 v207, v[22:23], s[74:75] offset:32
	v_pk_fma_f32 v[28:29], v[28:29], v[184:185], v[92:93]
	v_pk_fma_f32 v[26:27], v[26:27], v[182:183], v[90:91]
	s_nop 0
	v_cvt_pk_bf16_f32 v26, v26, v27
	v_cvt_pk_bf16_f32 v27, v28, v29
	global_store_dwordx2 v207, v[26:27], s[74:75] offset:64
	v_pk_fma_f32 v[32:33], v[32:33], v[188:189], v[96:97]
	v_pk_fma_f32 v[30:31], v[30:31], v[186:187], v[94:95]
	s_nop 0
	v_cvt_pk_bf16_f32 v30, v30, v31
	v_cvt_pk_bf16_f32 v31, v32, v33
	global_store_dwordx2 v207, v[30:31], s[74:75] offset:96
	v_pk_fma_f32 v[36:37], v[36:37], v[176:177], v[100:101]
	v_pk_fma_f32 v[34:35], v[34:35], v[174:175], v[98:99]
	s_nop 0
	v_cvt_pk_bf16_f32 v34, v34, v35
	v_cvt_pk_bf16_f32 v35, v36, v37
	global_store_dwordx2 v208, v[34:35], s[74:75] offset:0
	v_pk_fma_f32 v[40:41], v[40:41], v[180:181], v[104:105]
	v_pk_fma_f32 v[38:39], v[38:39], v[178:179], v[102:103]
	s_nop 0
	v_cvt_pk_bf16_f32 v38, v38, v39
	v_cvt_pk_bf16_f32 v39, v40, v41
	global_store_dwordx2 v208, v[38:39], s[74:75] offset:32
	v_pk_fma_f32 v[44:45], v[44:45], v[184:185], v[108:109]
	v_pk_fma_f32 v[42:43], v[42:43], v[182:183], v[106:107]
	s_nop 0
	v_cvt_pk_bf16_f32 v42, v42, v43
	v_cvt_pk_bf16_f32 v43, v44, v45
	global_store_dwordx2 v208, v[42:43], s[74:75] offset:64
	v_pk_fma_f32 v[48:49], v[48:49], v[188:189], v[112:113]
	v_pk_fma_f32 v[46:47], v[46:47], v[186:187], v[110:111]
	s_nop 0
	v_cvt_pk_bf16_f32 v46, v46, v47
	v_cvt_pk_bf16_f32 v47, v48, v49
	global_store_dwordx2 v208, v[46:47], s[74:75] offset:96
	v_pk_fma_f32 v[52:53], v[52:53], v[176:177], v[116:117]
	v_pk_fma_f32 v[50:51], v[50:51], v[174:175], v[114:115]
	s_nop 0
	v_cvt_pk_bf16_f32 v50, v50, v51
	v_cvt_pk_bf16_f32 v51, v52, v53
	global_store_dwordx2 v209, v[50:51], s[74:75] offset:0
	v_pk_fma_f32 v[56:57], v[56:57], v[180:181], v[120:121]
	v_pk_fma_f32 v[54:55], v[54:55], v[178:179], v[118:119]
	s_nop 0
	v_cvt_pk_bf16_f32 v54, v54, v55
	v_cvt_pk_bf16_f32 v55, v56, v57
	global_store_dwordx2 v209, v[54:55], s[74:75] offset:32
	v_pk_fma_f32 v[60:61], v[60:61], v[184:185], v[124:125]
	v_pk_fma_f32 v[58:59], v[58:59], v[182:183], v[122:123]
	s_nop 0
	v_cvt_pk_bf16_f32 v58, v58, v59
	v_cvt_pk_bf16_f32 v59, v60, v61
	global_store_dwordx2 v209, v[58:59], s[74:75] offset:64
	v_pk_fma_f32 v[64:65], v[64:65], v[188:189], v[128:129]
	v_pk_fma_f32 v[62:63], v[62:63], v[186:187], v[126:127]
	s_nop 0
	v_cvt_pk_bf16_f32 v62, v62, v63
	v_cvt_pk_bf16_f32 v63, v64, v65
	global_store_dwordx2 v209, v[62:63], s[74:75] offset:96
	s_branch .Lop_cvdone
.Lop_cvbf:
	v_lshlrev_b32_e32 v68, 16, v67
	v_and_b32_e32 v69, 0xffff0000, v67
	v_and_b32_e32 v67, 0xffff0000, v66
	v_lshlrev_b32_e32 v66, 16, v66
	v_pk_fma_f32 v[4:5], v[4:5], v[176:177], v[68:69]
	v_pk_fma_f32 v[2:3], v[2:3], v[174:175], v[66:67]
	s_nop 0
	v_cvt_pk_bf16_f32 v2, v2, v3
	v_cvt_pk_bf16_f32 v3, v4, v5
	global_store_dwordx2 v206, v[2:3], s[74:75] offset:0
	v_lshlrev_b32_e32 v72, 16, v71
	v_and_b32_e32 v73, 0xffff0000, v71
	v_and_b32_e32 v71, 0xffff0000, v70
	v_lshlrev_b32_e32 v70, 16, v70
	v_pk_fma_f32 v[8:9], v[8:9], v[180:181], v[72:73]
	v_pk_fma_f32 v[6:7], v[6:7], v[178:179], v[70:71]
	s_nop 0
	v_cvt_pk_bf16_f32 v6, v6, v7
	v_cvt_pk_bf16_f32 v7, v8, v9
	global_store_dwordx2 v206, v[6:7], s[74:75] offset:32
	v_lshlrev_b32_e32 v76, 16, v75
	v_and_b32_e32 v77, 0xffff0000, v75
	v_and_b32_e32 v75, 0xffff0000, v74
	v_lshlrev_b32_e32 v74, 16, v74
	v_pk_fma_f32 v[12:13], v[12:13], v[184:185], v[76:77]
	v_pk_fma_f32 v[10:11], v[10:11], v[182:183], v[74:75]
	s_nop 0
	v_cvt_pk_bf16_f32 v10, v10, v11
	v_cvt_pk_bf16_f32 v11, v12, v13
	global_store_dwordx2 v206, v[10:11], s[74:75] offset:64
	v_lshlrev_b32_e32 v80, 16, v79
	v_and_b32_e32 v81, 0xffff0000, v79
	v_and_b32_e32 v79, 0xffff0000, v78
	v_lshlrev_b32_e32 v78, 16, v78
	v_pk_fma_f32 v[16:17], v[16:17], v[188:189], v[80:81]
	v_pk_fma_f32 v[14:15], v[14:15], v[186:187], v[78:79]
	s_nop 0
	v_cvt_pk_bf16_f32 v14, v14, v15
	v_cvt_pk_bf16_f32 v15, v16, v17
	global_store_dwordx2 v206, v[14:15], s[74:75] offset:96
	v_lshlrev_b32_e32 v84, 16, v83
	v_and_b32_e32 v85, 0xffff0000, v83
	v_and_b32_e32 v83, 0xffff0000, v82
	v_lshlrev_b32_e32 v82, 16, v82
	v_pk_fma_f32 v[20:21], v[20:21], v[176:177], v[84:85]
	v_pk_fma_f32 v[18:19], v[18:19], v[174:175], v[82:83]
	s_nop 0
	v_cvt_pk_bf16_f32 v18, v18, v19
	v_cvt_pk_bf16_f32 v19, v20, v21
	global_store_dwordx2 v207, v[18:19], s[74:75] offset:0
	v_lshlrev_b32_e32 v88, 16, v87
	v_and_b32_e32 v89, 0xffff0000, v87
	v_and_b32_e32 v87, 0xffff0000, v86
	v_lshlrev_b32_e32 v86, 16, v86
	v_pk_fma_f32 v[24:25], v[24:25], v[180:181], v[88:89]
	v_pk_fma_f32 v[22:23], v[22:23], v[178:179], v[86:87]
	s_nop 0
	v_cvt_pk_bf16_f32 v22, v22, v23
	v_cvt_pk_bf16_f32 v23, v24, v25
	global_store_dwordx2 v207, v[22:23], s[74:75] offset:32
	v_lshlrev_b32_e32 v92, 16, v91
	v_and_b32_e32 v93, 0xffff0000, v91
	v_and_b32_e32 v91, 0xffff0000, v90
	v_lshlrev_b32_e32 v90, 16, v90
	v_pk_fma_f32 v[28:29], v[28:29], v[184:185], v[92:93]
	v_pk_fma_f32 v[26:27], v[26:27], v[182:183], v[90:91]
	s_nop 0
	v_cvt_pk_bf16_f32 v26, v26, v27
	v_cvt_pk_bf16_f32 v27, v28, v29
	global_store_dwordx2 v207, v[26:27], s[74:75] offset:64
	v_lshlrev_b32_e32 v96, 16, v95
	v_and_b32_e32 v97, 0xffff0000, v95
	v_and_b32_e32 v95, 0xffff0000, v94
	v_lshlrev_b32_e32 v94, 16, v94
	v_pk_fma_f32 v[32:33], v[32:33], v[188:189], v[96:97]
	v_pk_fma_f32 v[30:31], v[30:31], v[186:187], v[94:95]
	s_nop 0
	v_cvt_pk_bf16_f32 v30, v30, v31
	v_cvt_pk_bf16_f32 v31, v32, v33
	global_store_dwordx2 v207, v[30:31], s[74:75] offset:96
	v_lshlrev_b32_e32 v100, 16, v99
	v_and_b32_e32 v101, 0xffff0000, v99
	v_and_b32_e32 v99, 0xffff0000, v98
	v_lshlrev_b32_e32 v98, 16, v98
	v_pk_fma_f32 v[36:37], v[36:37], v[176:177], v[100:101]
	v_pk_fma_f32 v[34:35], v[34:35], v[174:175], v[98:99]
	s_nop 0
	v_cvt_pk_bf16_f32 v34, v34, v35
	v_cvt_pk_bf16_f32 v35, v36, v37
	global_store_dwordx2 v208, v[34:35], s[74:75] offset:0
	v_lshlrev_b32_e32 v104, 16, v103
	v_and_b32_e32 v105, 0xffff0000, v103
	v_and_b32_e32 v103, 0xffff0000, v102
	v_lshlrev_b32_e32 v102, 16, v102
	v_pk_fma_f32 v[40:41], v[40:41], v[180:181], v[104:105]
	v_pk_fma_f32 v[38:39], v[38:39], v[178:179], v[102:103]
	s_nop 0
	v_cvt_pk_bf16_f32 v38, v38, v39
	v_cvt_pk_bf16_f32 v39, v40, v41
	global_store_dwordx2 v208, v[38:39], s[74:75] offset:32
	v_lshlrev_b32_e32 v108, 16, v107
	v_and_b32_e32 v109, 0xffff0000, v107
	v_and_b32_e32 v107, 0xffff0000, v106
	v_lshlrev_b32_e32 v106, 16, v106
	v_pk_fma_f32 v[44:45], v[44:45], v[184:185], v[108:109]
	v_pk_fma_f32 v[42:43], v[42:43], v[182:183], v[106:107]
	s_nop 0
	v_cvt_pk_bf16_f32 v42, v42, v43
	v_cvt_pk_bf16_f32 v43, v44, v45
	global_store_dwordx2 v208, v[42:43], s[74:75] offset:64
	v_lshlrev_b32_e32 v112, 16, v111
	v_and_b32_e32 v113, 0xffff0000, v111
	v_and_b32_e32 v111, 0xffff0000, v110
	v_lshlrev_b32_e32 v110, 16, v110
	v_pk_fma_f32 v[48:49], v[48:49], v[188:189], v[112:113]
	v_pk_fma_f32 v[46:47], v[46:47], v[186:187], v[110:111]
	s_nop 0
	v_cvt_pk_bf16_f32 v46, v46, v47
	v_cvt_pk_bf16_f32 v47, v48, v49
	global_store_dwordx2 v208, v[46:47], s[74:75] offset:96
	v_lshlrev_b32_e32 v116, 16, v115
	v_and_b32_e32 v117, 0xffff0000, v115
	v_and_b32_e32 v115, 0xffff0000, v114
	v_lshlrev_b32_e32 v114, 16, v114
	v_pk_fma_f32 v[52:53], v[52:53], v[176:177], v[116:117]
	v_pk_fma_f32 v[50:51], v[50:51], v[174:175], v[114:115]
	s_nop 0
	v_cvt_pk_bf16_f32 v50, v50, v51
	v_cvt_pk_bf16_f32 v51, v52, v53
	global_store_dwordx2 v209, v[50:51], s[74:75] offset:0
	v_lshlrev_b32_e32 v120, 16, v119
	v_and_b32_e32 v121, 0xffff0000, v119
	v_and_b32_e32 v119, 0xffff0000, v118
	v_lshlrev_b32_e32 v118, 16, v118
	v_pk_fma_f32 v[56:57], v[56:57], v[180:181], v[120:121]
	v_pk_fma_f32 v[54:55], v[54:55], v[178:179], v[118:119]
	s_nop 0
	v_cvt_pk_bf16_f32 v54, v54, v55
	v_cvt_pk_bf16_f32 v55, v56, v57
	global_store_dwordx2 v209, v[54:55], s[74:75] offset:32
	v_lshlrev_b32_e32 v124, 16, v123
	v_and_b32_e32 v125, 0xffff0000, v123
	v_and_b32_e32 v123, 0xffff0000, v122
	v_lshlrev_b32_e32 v122, 16, v122
	v_pk_fma_f32 v[60:61], v[60:61], v[184:185], v[124:125]
	v_pk_fma_f32 v[58:59], v[58:59], v[182:183], v[122:123]
	s_nop 0
	v_cvt_pk_bf16_f32 v58, v58, v59
	v_cvt_pk_bf16_f32 v59, v60, v61
	global_store_dwordx2 v209, v[58:59], s[74:75] offset:64
	v_lshlrev_b32_e32 v128, 16, v127
	v_and_b32_e32 v129, 0xffff0000, v127
	v_and_b32_e32 v127, 0xffff0000, v126
	v_lshlrev_b32_e32 v126, 16, v126
	v_pk_fma_f32 v[64:65], v[64:65], v[188:189], v[128:129]
	v_pk_fma_f32 v[62:63], v[62:63], v[186:187], v[126:127]
	s_nop 0
	v_cvt_pk_bf16_f32 v62, v62, v63
	v_cvt_pk_bf16_f32 v63, v64, v65
	global_store_dwordx2 v209, v[62:63], s[74:75] offset:96
.Lop_cvdone:
	s_add_u32 s78, s78, s79
	s_cmp_gt_u32 s78, 31
	s_cbranch_scc1 .Lop_exit
	s_barrier
	s_branch .Lop_tile
.Lop_exit:
	v_mov_b32_e32 v163, 0
	v_mov_b32_e32 v164, 0x358637bd
	v_mov_b32_e32 v165, 1
	v_mov_b32_e32 v168, 0x2bf
	v_mov_b32_e32 v169, 0
	v_mov_b32_e32 v170, 0x340
	v_mov_b32_e32 v171, 0
	v_mov_b32_e32 v172, 0x33f
	v_mov_b32_e32 v173, 0
	v_mov_b32_e32 v202, 0xc00
	v_mov_b32_e32 v203, 0x7ffffc00
	v_mov_b32_e32 v204, 0xffffff00
	v_mov_b32_e32 v205, 0x400
	v_mov_b32_e32 v206, 0x100
	v_mov_b32_e32 v207, 0x3ff
	v_mov_b32_e32 v208, 0xff
	v_mov_b32_e32 v209, 0xcf
	v_mov_b32_e32 v210, 0xdf
	v_mov_b32_e32 v211, 0xef
	v_mbcnt_lo_u32_b32 v194, -1, 0
	v_mbcnt_hi_u32_b32 v194, -1, v194
	v_and_b32_e32 v195, 64, v194
	v_add_u32_e32 v195, 64, v195
	v_xor_b32_e32 v196, 32, v194
	v_xor_b32_e32 v197, 16, v194
	v_xor_b32_e32 v198, 8, v194
	v_xor_b32_e32 v199, 4, v194
	v_xor_b32_e32 v200, 2, v194
	v_xor_b32_e32 v201, 1, v194
	s_branch .LBB0_312
.LBB0_211:
	v_readlane_b32 s46, v252, 11
	v_readlane_b32 s47, v252, 12
	s_mov_b64 s[2:3], 0

.LBB0_230:
	v_readlane_b32 s36, v254, 30
	s_mov_b64 s[2:3], 0
	s_mov_b64 s[88:89], -1
	v_readlane_b32 s37, v254, 31
	s_branch .LBB0_311
.LBB0_309:
	s_mov_b64 s[0:1], -1
	v_writelane_b32 v252, s0, 6
	s_waitcnt lgkmcnt(0)
	s_barrier
	v_writelane_b32 v252, s1, 7
	s_mov_b64 s[2:3], 0
